# GEMM units after the first: the first two load-segment waits of the peeled K-iteration no longer count vector memory (the epilogue already drained every staged tile), so the epilogue's stores need not
# baseline (speedup 1.0000x reference)
.LBB0_312:
	s_add_u32 s22, s14, 0x200000
	s_addc_u32 s23, s15, 0
	s_add_u32 s24, s14, 0x300000
	s_addc_u32 s25, s15, 0
	s_add_u32 s26, s14, 0x4800000
	s_addc_u32 s27, s15, 0
	s_add_u32 s28, s14, 0x8800000
	s_addc_u32 s29, s15, 0
	s_add_u32 s30, s14, 0xc800000
	s_addc_u32 s31, s15, 0
	s_add_u32 s14, s14, 0x14800000
	s_addc_u32 s15, s15, 0
	s_lshl_b32 s65, s4, 6
	s_lshl_b32 s66, s4, 13
	s_lshl_b32 s4, s5, 5
	s_mov_b64 s[36:37], 0x80
	s_and_b32 s67, s4, 0x60
	s_add_i32 m0, s17, 0x18000
	v_lshl_add_u64 v[6:7], v[6:7], 0, s[36:37]
	s_lshl_b32 s38, s67, 7
	s_waitcnt vmcnt(2)
	s_barrier
	global_load_lds_dwordx4 v[6:7], off
	v_lshl_add_u64 v[4:5], v[4:5], 0, s[36:37]
	s_add_i32 m0, s17, 0x1a000
	s_add_i32 s68, s17, 0x8000
	s_add_i32 s69, s17, 0xa000
	global_load_lds_dwordx4 v[4:5], off
	v_lshl_add_u64 v[0:1], v[0:1], 0, s[36:37]
	s_mov_b32 m0, s68
	s_add_u32 s4, s8, 0x40080
	global_load_lds_dwordx4 v[0:1], off
	v_lshl_add_u64 v[0:1], v[2:3], 0, s[36:37]
	s_mov_b32 m0, s69
	s_addc_u32 s5, s9, 0
	global_load_lds_dwordx4 v[0:1], off
	s_add_i32 m0, s17, 0x1c000
	v_lshl_add_u64 v[0:1], s[4:5], 0, v[162:163]
	global_load_lds_dwordx4 v[0:1], off
	v_lshl_add_u64 v[0:1], s[4:5], 0, v[166:167]
	s_add_i32 m0, s17, 0x1e000
	s_movk_i32 s4, 0x3c0
	global_load_lds_dwordx4 v[0:1], off
	v_and_b32_e32 v0, 48, v8
	v_lshlrev_b32_e32 v1, 6, v8
	v_and_or_b32 v0, v1, s4, v0
	v_lshlrev_b32_e32 v1, 2, v8
	v_and_b32_e32 v1, 32, v1
	v_bitop3_b32 v2, v0, s66, v1 bitop3:0xde
	v_bitop3_b32 v208, s38, v0, v1 bitop3:0xf6
	v_lshlrev_b32_e32 v0, 14, v9
	v_and_b32_e32 v0, 0xffff8000, v0
	v_lshl_add_u32 v0, v10, 11, v0
	v_and_b32_e32 v1, 1, v9
	v_lshl_or_b32 v0, v1, 6, v0
	v_lshl_add_u32 v170, v11, 1, v0
	v_lshlrev_b32_e32 v0, 14, v12
	v_and_b32_e32 v0, 0xffff8000, v0
	s_waitcnt vmcnt(0)
	s_cmpk_lt_u32 s18, 0x100
	v_lshl_add_u32 v0, v13, 11, v0
	v_and_b32_e32 v1, 1, v12
	s_cselect_b64 s[38:39], -1, 0
	v_lshl_or_b32 v0, v1, 6, v0
	s_add_i32 s73, 0, 0x10000
	s_add_i32 s74, 0, 0x14000
	s_movk_i32 s40, 0xe000
	s_add_i32 s70, s66, 0x4000
	s_ashr_i32 s71, s58, 31
	v_mov_b32_e32 v171, v169
	v_lshl_add_u32 v172, v14, 1, v0
	v_mov_b32_e32 v173, v169
	v_mov_b64_e32 v[174:175], 0xc00
	v_mov_b64_e32 v[176:177], 0xbff
	s_movk_i32 s72, 0x181
	v_add_u32_e32 v209, s73, v208
	v_add_u32_e32 v210, s74, v208
	v_add_u32_e32 v211, 0, v2
	v_mov_b32_e32 v212, 0x358637bd
	s_mov_b32 s41, -1
	s_movk_i32 s75, 0xe000
	s_mov_b32 s76, 0xc2fc0000
	v_mov_b32_e32 v213, 0xbbb906ce
	v_mov_b32_e32 v214, 0xbc3963dd
	v_mov_b32_e32 v215, 0x42800000
	v_not_b32_e32 v216, 63
	s_mov_b32 s5, 0
	s_barrier
	s_branch .LBB0_315

.LBB0_322:
	s_ashr_i32 s43, s42, 31
	s_lshl_b64 s[46:47], s[42:43], 19
	s_add_u32 s46, s12, s46
	s_addc_u32 s47, s13, s47
	s_and_b64 s[48:49], s[4:5], exec
	s_cselect_b32 s18, s47, s7
	s_cselect_b32 s43, s46, s6
	s_ashr_i32 s45, s44, 31
	s_lshl_b64 s[48:49], s[44:45], 19
	s_add_u32 s48, s59, s48
	s_addc_u32 s49, s60, s49
	s_and_b64 s[50:51], s[4:5], exec
	s_cselect_b32 s45, s49, s9
	s_cselect_b32 s55, s48, s8
	s_add_u32 s6, s6, 0x40080
	s_addc_u32 s7, s7, 0
	s_add_u32 s56, s8, 0x100
	s_addc_u32 s57, s9, 0
	s_mov_b32 s78, -2
	ds_read_b128 v[96:99], v209
	ds_read_b128 v[100:103], v209 offset:1024
	ds_read_b128 v[120:123], v209 offset:2048
	ds_read_b128 v[124:127], v209 offset:3072
	ds_read_b128 v[144:147], v210
	ds_read_b128 v[148:151], v210 offset:1024
	ds_read_b128 v[152:155], v210 offset:2048
	ds_read_b128 v[156:159], v210 offset:3072
	s_add_u32 s8, s6, 0xfffc0080
	s_addc_u32 s9, s7, -1
	s_cmp_eq_u32 s78, 12
	s_cselect_b32 s51, s18, s9
	s_cselect_b32 s50, s43, s8
	s_cselect_b32 s9, s45, s57
	s_cselect_b32 s8, s55, s56
	v_lshl_add_u64 v[206:207], s[6:7], 0, v[170:171]
	s_add_i32 m0, s17, 0xc000
	ds_read_b128 v[178:181], v211
	ds_read_b128 v[182:185], v211 offset:1024
	ds_read_b128 v[186:189], v211 offset:2048
	ds_read_b128 v[190:193], v211 offset:3072
	ds_read_b128 v[194:197], v211 offset:4096
	ds_read_b128 v[198:201], v211 offset:5120
	ds_read_b128 v[202:205], v211 offset:6144
	ds_read_b128 v[218:221], v211 offset:7168
	global_load_lds_dwordx4 v[206:207], off
	s_add_i32 m0, s17, 0xe000
	v_lshl_add_u64 v[206:207], s[6:7], 0, v[172:173]
	global_load_lds_dwordx4 v[206:207], off
	s_waitcnt lgkmcnt(0)
	s_barrier
	s_setprio 1
	v_mfma_f32_16x16x32_bf16 v[140:143], v[96:99], v[178:181], 0
	v_mfma_f32_16x16x32_bf16 v[136:139], v[120:123], v[178:181], 0
	v_mfma_f32_16x16x32_bf16 v[116:119], v[96:99], v[186:189], 0
	v_mfma_f32_16x16x32_bf16 v[112:115], v[120:123], v[186:189], 0
	v_mfma_f32_16x16x32_bf16 v[92:95], v[96:99], v[194:197], 0
	v_mfma_f32_16x16x32_bf16 v[88:91], v[120:123], v[194:197], 0
	v_mfma_f32_16x16x32_bf16 v[76:79], v[96:99], v[202:205], 0
	v_mfma_f32_16x16x32_bf16 v[72:75], v[120:123], v[202:205], 0
	v_mfma_f32_16x16x32_bf16 v[140:143], v[100:103], v[182:185], v[140:143]
	v_mfma_f32_16x16x32_bf16 v[136:139], v[124:127], v[182:185], v[136:139]
	v_mfma_f32_16x16x32_bf16 v[116:119], v[100:103], v[190:193], v[116:119]
	v_mfma_f32_16x16x32_bf16 v[112:115], v[124:127], v[190:193], v[112:115]
	v_mfma_f32_16x16x32_bf16 v[92:95], v[100:103], v[198:201], v[92:95]
	v_mfma_f32_16x16x32_bf16 v[88:91], v[124:127], v[198:201], v[88:91]
	v_mfma_f32_16x16x32_bf16 v[76:79], v[100:103], v[218:221], v[76:79]
	v_mfma_f32_16x16x32_bf16 v[72:75], v[124:127], v[218:221], v[72:75]
	v_mfma_f32_16x16x32_bf16 v[132:135], v[144:147], v[178:181], 0
	v_mfma_f32_16x16x32_bf16 v[128:131], v[152:155], v[178:181], 0
	v_mfma_f32_16x16x32_bf16 v[108:111], v[144:147], v[186:189], 0
	v_mfma_f32_16x16x32_bf16 v[104:107], v[152:155], v[186:189], 0
	v_mfma_f32_16x16x32_bf16 v[84:87], v[144:147], v[194:197], 0
	v_mfma_f32_16x16x32_bf16 v[80:83], v[152:155], v[194:197], 0
	v_mfma_f32_16x16x32_bf16 v[68:71], v[144:147], v[202:205], 0
	v_mfma_f32_16x16x32_bf16 v[64:67], v[152:155], v[202:205], 0
	v_mfma_f32_16x16x32_bf16 v[132:135], v[148:151], v[182:185], v[132:135]
	v_mfma_f32_16x16x32_bf16 v[128:131], v[156:159], v[182:185], v[128:131]
	v_mfma_f32_16x16x32_bf16 v[108:111], v[148:151], v[190:193], v[108:111]
	v_mfma_f32_16x16x32_bf16 v[104:107], v[156:159], v[190:193], v[104:107]
	s_setprio 2
	s_barrier
	v_mfma_f32_16x16x32_bf16 v[84:87], v[148:151], v[198:201], v[84:87]
	v_mfma_f32_16x16x32_bf16 v[80:83], v[156:159], v[198:201], v[80:83]
	v_mfma_f32_16x16x32_bf16 v[68:71], v[148:151], v[218:221], v[68:71]
	v_mfma_f32_16x16x32_bf16 v[64:67], v[156:159], v[218:221], v[64:67]
	s_setprio 2
	s_add_i32 s79, s73, s61
	v_lshl_add_u64 v[206:207], s[8:9], 0, v[162:163]
	s_mov_b32 m0, s79
	ds_read_b128 v[178:181], v211 offset:16384
	ds_read_b128 v[182:185], v211 offset:17408
	ds_read_b128 v[186:189], v211 offset:18432
	ds_read_b128 v[190:193], v211 offset:19456
	ds_read_b128 v[194:197], v211 offset:20480
	ds_read_b128 v[198:201], v211 offset:21504
	ds_read_b128 v[202:205], v211 offset:22528
	ds_read_b128 v[218:221], v211 offset:23552
	global_load_lds_dwordx4 v[206:207], off
	s_add_i32 m0, s79, 0x2000
	s_add_u32 s80, s8, 0x40000
	v_lshl_add_u64 v[222:223], s[8:9], 0, v[166:167]
	s_addc_u32 s81, s9, 0
	s_add_i32 s79, s74, s61
	global_load_lds_dwordx4 v[222:223], off
	v_lshl_add_u64 v[224:225], s[80:81], 0, v[162:163]
	s_mov_b32 m0, s79
	v_lshl_add_u64 v[226:227], s[50:51], 0, v[164:165]
	global_load_lds_dwordx4 v[224:225], off
	s_add_i32 m0, s79, 0x2000
	v_lshl_add_u64 v[224:225], s[80:81], 0, v[166:167]
	global_load_lds_dwordx4 v[224:225], off
	s_mov_b32 m0, s17
	v_lshl_add_u64 v[224:225], s[50:51], 0, v[160:161]
	global_load_lds_dwordx4 v[224:225], off
	s_mov_b32 m0, s62
	s_nop 0
	global_load_lds_dwordx4 v[226:227], off
	s_waitcnt lgkmcnt(0)
	s_barrier
	s_setprio 1
	v_mfma_f32_16x16x32_bf16 v[60:63], v[96:99], v[178:181], 0
	v_mfma_f32_16x16x32_bf16 v[56:59], v[120:123], v[178:181], 0
	v_mfma_f32_16x16x32_bf16 v[44:47], v[96:99], v[186:189], 0
	v_mfma_f32_16x16x32_bf16 v[40:43], v[120:123], v[186:189], 0
	v_mfma_f32_16x16x32_bf16 v[28:31], v[96:99], v[194:197], 0
	v_mfma_f32_16x16x32_bf16 v[24:27], v[120:123], v[194:197], 0
	v_mfma_f32_16x16x32_bf16 v[12:15], v[96:99], v[202:205], 0
	v_mfma_f32_16x16x32_bf16 v[8:11], v[120:123], v[202:205], 0
	v_mfma_f32_16x16x32_bf16 v[60:63], v[100:103], v[182:185], v[60:63]
	v_mfma_f32_16x16x32_bf16 v[56:59], v[124:127], v[182:185], v[56:59]
	v_mfma_f32_16x16x32_bf16 v[44:47], v[100:103], v[190:193], v[44:47]
	v_mfma_f32_16x16x32_bf16 v[40:43], v[124:127], v[190:193], v[40:43]
	v_mfma_f32_16x16x32_bf16 v[28:31], v[100:103], v[198:201], v[28:31]
	v_mfma_f32_16x16x32_bf16 v[24:27], v[124:127], v[198:201], v[24:27]
	v_mfma_f32_16x16x32_bf16 v[12:15], v[100:103], v[218:221], v[12:15]
	v_mfma_f32_16x16x32_bf16 v[8:11], v[124:127], v[218:221], v[8:11]
	v_mfma_f32_16x16x32_bf16 v[52:55], v[144:147], v[178:181], 0
	v_mfma_f32_16x16x32_bf16 v[48:51], v[152:155], v[178:181], 0
	v_mfma_f32_16x16x32_bf16 v[36:39], v[144:147], v[186:189], 0
	v_mfma_f32_16x16x32_bf16 v[32:35], v[152:155], v[186:189], 0
	v_mfma_f32_16x16x32_bf16 v[20:23], v[144:147], v[194:197], 0
	v_mfma_f32_16x16x32_bf16 v[16:19], v[152:155], v[194:197], 0
	v_mfma_f32_16x16x32_bf16 v[4:7], v[144:147], v[202:205], 0
	v_mfma_f32_16x16x32_bf16 v[0:3], v[152:155], v[202:205], 0
	v_mfma_f32_16x16x32_bf16 v[52:55], v[148:151], v[182:185], v[52:55]
	v_mfma_f32_16x16x32_bf16 v[48:51], v[156:159], v[182:185], v[48:51]
	v_mfma_f32_16x16x32_bf16 v[36:39], v[148:151], v[190:193], v[36:39]
	v_mfma_f32_16x16x32_bf16 v[32:35], v[156:159], v[190:193], v[32:35]
	s_setprio 2
	s_barrier
	v_mfma_f32_16x16x32_bf16 v[20:23], v[148:151], v[198:201], v[20:23]
	v_mfma_f32_16x16x32_bf16 v[16:19], v[156:159], v[198:201], v[16:19]
	v_mfma_f32_16x16x32_bf16 v[4:7], v[148:151], v[218:221], v[4:7]
	v_mfma_f32_16x16x32_bf16 v[0:3], v[156:159], v[218:221], v[0:3]
	s_setprio 0
	s_add_i32 s79, 0, 0x18000
	s_add_i32 s80, 0, 0x1c000
	v_add_u32_e32 v124, s79, v208
	v_add_u32_e32 v156, s80, v208
	ds_read_b128 v[96:99], v124
	ds_read_b128 v[100:103], v124 offset:1024
	ds_read_b128 v[120:123], v124 offset:2048
	ds_read_b128 v[124:127], v124 offset:3072
	ds_read_b128 v[144:147], v156
	ds_read_b128 v[148:151], v156 offset:1024
	ds_read_b128 v[152:155], v156 offset:2048
	ds_read_b128 v[156:159], v156 offset:3072
	s_add_u32 s50, s50, 0x40000
	s_addc_u32 s51, s51, 0
	s_mov_b32 m0, s63
	v_lshl_add_u64 v[228:229], s[50:51], 0, v[160:161]
	ds_read_b128 v[178:181], v211 offset:32768
	ds_read_b128 v[182:185], v211 offset:33792
	ds_read_b128 v[186:189], v211 offset:34816
	ds_read_b128 v[190:193], v211 offset:35840
	ds_read_b128 v[194:197], v211 offset:36864
	ds_read_b128 v[198:201], v211 offset:37888
	ds_read_b128 v[202:205], v211 offset:38912
	ds_read_b128 v[218:221], v211 offset:39936
	global_load_lds_dwordx4 v[228:229], off
	s_mov_b32 m0, s64
	v_lshl_add_u64 v[228:229], s[50:51], 0, v[164:165]
	global_load_lds_dwordx4 v[228:229], off
	s_waitcnt vmcnt(8) lgkmcnt(0)
	s_barrier
	s_setprio 1
	v_mfma_f32_16x16x32_bf16 v[140:143], v[96:99], v[178:181], v[140:143]
	v_mfma_f32_16x16x32_bf16 v[136:139], v[120:123], v[178:181], v[136:139]
	v_mfma_f32_16x16x32_bf16 v[116:119], v[96:99], v[186:189], v[116:119]
	v_mfma_f32_16x16x32_bf16 v[112:115], v[120:123], v[186:189], v[112:115]
	v_mfma_f32_16x16x32_bf16 v[92:95], v[96:99], v[194:197], v[92:95]
	v_mfma_f32_16x16x32_bf16 v[88:91], v[120:123], v[194:197], v[88:91]
	v_mfma_f32_16x16x32_bf16 v[76:79], v[96:99], v[202:205], v[76:79]
	v_mfma_f32_16x16x32_bf16 v[72:75], v[120:123], v[202:205], v[72:75]
	v_mfma_f32_16x16x32_bf16 v[140:143], v[100:103], v[182:185], v[140:143]
	v_mfma_f32_16x16x32_bf16 v[136:139], v[124:127], v[182:185], v[136:139]
	v_mfma_f32_16x16x32_bf16 v[116:119], v[100:103], v[190:193], v[116:119]
	v_mfma_f32_16x16x32_bf16 v[112:115], v[124:127], v[190:193], v[112:115]
	v_mfma_f32_16x16x32_bf16 v[92:95], v[100:103], v[198:201], v[92:95]
	v_mfma_f32_16x16x32_bf16 v[88:91], v[124:127], v[198:201], v[88:91]
	v_mfma_f32_16x16x32_bf16 v[76:79], v[100:103], v[218:221], v[76:79]
	v_mfma_f32_16x16x32_bf16 v[72:75], v[124:127], v[218:221], v[72:75]
	v_mfma_f32_16x16x32_bf16 v[132:135], v[144:147], v[178:181], v[132:135]
	v_mfma_f32_16x16x32_bf16 v[128:131], v[152:155], v[178:181], v[128:131]
	v_mfma_f32_16x16x32_bf16 v[108:111], v[144:147], v[186:189], v[108:111]
	v_mfma_f32_16x16x32_bf16 v[104:107], v[152:155], v[186:189], v[104:107]
	v_mfma_f32_16x16x32_bf16 v[84:87], v[144:147], v[194:197], v[84:87]
	v_mfma_f32_16x16x32_bf16 v[80:83], v[152:155], v[194:197], v[80:83]
	v_mfma_f32_16x16x32_bf16 v[68:71], v[144:147], v[202:205], v[68:71]
	v_mfma_f32_16x16x32_bf16 v[64:67], v[152:155], v[202:205], v[64:67]
	v_mfma_f32_16x16x32_bf16 v[132:135], v[148:151], v[182:185], v[132:135]
	v_mfma_f32_16x16x32_bf16 v[128:131], v[156:159], v[182:185], v[128:131]
	v_mfma_f32_16x16x32_bf16 v[108:111], v[148:151], v[190:193], v[108:111]
	v_mfma_f32_16x16x32_bf16 v[104:107], v[156:159], v[190:193], v[104:107]
	s_setprio 2
	s_barrier
	v_mfma_f32_16x16x32_bf16 v[84:87], v[148:151], v[198:201], v[84:87]
	v_mfma_f32_16x16x32_bf16 v[80:83], v[156:159], v[198:201], v[80:83]
	v_mfma_f32_16x16x32_bf16 v[68:71], v[148:151], v[218:221], v[68:71]
	v_mfma_f32_16x16x32_bf16 v[64:67], v[156:159], v[218:221], v[64:67]
	s_setprio 2
	s_add_i32 s50, s79, s61
	v_lshl_add_u64 v[206:207], v[206:207], 0, s[36:37]
	s_mov_b32 m0, s50
	ds_read_b128 v[178:181], v211 offset:49152
	ds_read_b128 v[182:185], v211 offset:50176
	ds_read_b128 v[186:189], v211 offset:51200
	ds_read_b128 v[190:193], v211 offset:52224
	ds_read_b128 v[194:197], v211 offset:53248
	ds_read_b128 v[198:201], v211 offset:54272
	ds_read_b128 v[202:205], v211 offset:55296
	ds_read_b128 v[218:221], v211 offset:56320
	global_load_lds_dwordx4 v[206:207], off
	s_add_i32 m0, s50, 0x2000
	s_add_u32 s8, s8, 0x40080
	v_lshl_add_u64 v[206:207], v[222:223], 0, s[36:37]
	s_addc_u32 s9, s9, 0
	s_add_i32 s50, s80, s61
	global_load_lds_dwordx4 v[206:207], off
	s_mov_b32 m0, s50
	v_lshl_add_u64 v[206:207], s[8:9], 0, v[162:163]
	global_load_lds_dwordx4 v[206:207], off
	s_add_i32 m0, s50, 0x2000
	v_lshl_add_u64 v[206:207], s[8:9], 0, v[166:167]
	global_load_lds_dwordx4 v[206:207], off
	s_mov_b32 m0, s68
	v_lshl_add_u64 v[206:207], v[224:225], 0, s[36:37]
	global_load_lds_dwordx4 v[206:207], off
	s_mov_b32 m0, s69
	v_lshl_add_u64 v[206:207], v[226:227], 0, s[36:37]
	global_load_lds_dwordx4 v[206:207], off
	s_waitcnt vmcnt(8) lgkmcnt(0)
	s_barrier
	s_setprio 1
	v_mfma_f32_16x16x32_bf16 v[60:63], v[96:99], v[178:181], v[60:63]
	v_mfma_f32_16x16x32_bf16 v[56:59], v[120:123], v[178:181], v[56:59]
	v_mfma_f32_16x16x32_bf16 v[44:47], v[96:99], v[186:189], v[44:47]
	v_mfma_f32_16x16x32_bf16 v[40:43], v[120:123], v[186:189], v[40:43]
	v_mfma_f32_16x16x32_bf16 v[28:31], v[96:99], v[194:197], v[28:31]
	v_mfma_f32_16x16x32_bf16 v[24:27], v[120:123], v[194:197], v[24:27]
	v_mfma_f32_16x16x32_bf16 v[12:15], v[96:99], v[202:205], v[12:15]
	v_mfma_f32_16x16x32_bf16 v[8:11], v[120:123], v[202:205], v[8:11]
	v_mfma_f32_16x16x32_bf16 v[60:63], v[100:103], v[182:185], v[60:63]
	v_mfma_f32_16x16x32_bf16 v[56:59], v[124:127], v[182:185], v[56:59]
	v_mfma_f32_16x16x32_bf16 v[44:47], v[100:103], v[190:193], v[44:47]
	v_mfma_f32_16x16x32_bf16 v[40:43], v[124:127], v[190:193], v[40:43]
	v_mfma_f32_16x16x32_bf16 v[28:31], v[100:103], v[198:201], v[28:31]
	v_mfma_f32_16x16x32_bf16 v[24:27], v[124:127], v[198:201], v[24:27]
	v_mfma_f32_16x16x32_bf16 v[12:15], v[100:103], v[218:221], v[12:15]
	v_mfma_f32_16x16x32_bf16 v[8:11], v[124:127], v[218:221], v[8:11]
	v_mfma_f32_16x16x32_bf16 v[52:55], v[144:147], v[178:181], v[52:55]
	v_mfma_f32_16x16x32_bf16 v[48:51], v[152:155], v[178:181], v[48:51]
	v_mfma_f32_16x16x32_bf16 v[36:39], v[144:147], v[186:189], v[36:39]
	v_mfma_f32_16x16x32_bf16 v[32:35], v[152:155], v[186:189], v[32:35]
	v_mfma_f32_16x16x32_bf16 v[20:23], v[144:147], v[194:197], v[20:23]
	v_mfma_f32_16x16x32_bf16 v[16:19], v[152:155], v[194:197], v[16:19]
	v_mfma_f32_16x16x32_bf16 v[4:7], v[144:147], v[202:205], v[4:7]
	v_mfma_f32_16x16x32_bf16 v[0:3], v[152:155], v[202:205], v[0:3]
	v_mfma_f32_16x16x32_bf16 v[52:55], v[148:151], v[182:185], v[52:55]
	v_mfma_f32_16x16x32_bf16 v[48:51], v[156:159], v[182:185], v[48:51]
	v_mfma_f32_16x16x32_bf16 v[36:39], v[148:151], v[190:193], v[36:39]
	v_mfma_f32_16x16x32_bf16 v[32:35], v[156:159], v[190:193], v[32:35]
	s_setprio 2
	s_barrier
	v_mfma_f32_16x16x32_bf16 v[20:23], v[148:151], v[198:201], v[20:23]
	v_mfma_f32_16x16x32_bf16 v[16:19], v[156:159], v[198:201], v[16:19]
	v_mfma_f32_16x16x32_bf16 v[4:7], v[148:151], v[218:221], v[4:7]
	v_mfma_f32_16x16x32_bf16 v[0:3], v[156:159], v[218:221], v[0:3]
	s_setprio 0
	s_add_i32 s78, s78, 2
	s_add_u32 s6, s6, 0x100
	s_addc_u32 s7, s7, 0
	s_add_u32 s56, s56, 0x100
	s_addc_u32 s57, s57, 0
	s_cmp_gt_u32 s78, 13

.LBB0_778:
	s_add_u32 s12, s4, 0x100000
	s_addc_u32 s13, s5, 0
	s_add_u32 s14, s4, 0x4800000
	s_addc_u32 s15, s5, 0
	s_lshl_b32 s56, s17, 6
	s_lshl_b32 s19, s17, 13
	s_lshl_b32 s4, s16, 5
	s_mov_b64 s[16:17], 0x80
	s_and_b32 s20, s4, 0x60
	s_add_i32 m0, s50, 0x18000
	v_lshl_add_u64 v[6:7], v[6:7], 0, s[16:17]
	s_lshl_b32 s22, s20, 7
	s_waitcnt vmcnt(2)
	s_barrier
	global_load_lds_dwordx4 v[6:7], off
	v_lshl_add_u64 v[4:5], v[4:5], 0, s[16:17]
	s_add_i32 m0, s50, 0x1a000
	s_add_i32 s57, s50, 0x8000
	s_add_i32 s58, s50, 0xa000
	global_load_lds_dwordx4 v[4:5], off
	v_lshl_add_u64 v[0:1], v[0:1], 0, s[16:17]
	s_mov_b32 m0, s57
	s_add_u32 s4, s38, 0x40080
	global_load_lds_dwordx4 v[0:1], off
	v_lshl_add_u64 v[0:1], v[2:3], 0, s[16:17]
	s_mov_b32 m0, s58
	s_addc_u32 s5, s39, 0
	global_load_lds_dwordx4 v[0:1], off
	s_add_i32 m0, s50, 0x1c000
	v_lshl_add_u64 v[0:1], s[4:5], 0, v[132:133]
	global_load_lds_dwordx4 v[0:1], off
	v_lshl_add_u64 v[0:1], s[4:5], 0, v[128:129]
	s_add_i32 m0, s50, 0x1e000
	s_movk_i32 s4, 0x3c0
	global_load_lds_dwordx4 v[0:1], off
	v_and_b32_e32 v0, 48, v8
	v_lshlrev_b32_e32 v1, 6, v8
	v_and_or_b32 v0, v1, s4, v0
	v_lshlrev_b32_e32 v1, 2, v8
	v_and_b32_e32 v1, 32, v1
	v_bitop3_b32 v2, v0, s19, v1 bitop3:0xde
	v_bitop3_b32 v162, s22, v0, v1 bitop3:0xf6
	v_lshlrev_b32_e32 v0, 14, v13
	v_and_b32_e32 v0, 0xffff8000, v0
	v_lshl_add_u32 v0, v12, 11, v0
	v_and_b32_e32 v1, 1, v13
	v_lshl_or_b32 v0, v1, 6, v0
	v_lshl_add_u32 v136, v14, 1, v0
	v_lshlrev_b32_e32 v0, 14, v9
	v_and_b32_e32 v0, 0xffff8000, v0
	s_waitcnt vmcnt(0)
	s_cmpk_lt_u32 s18, 0x100
	v_lshl_add_u32 v0, v10, 11, v0
	v_and_b32_e32 v1, 1, v9
	s_cselect_b64 s[18:19], -1, 0
	v_lshl_or_b32 v0, v1, 6, v0
	s_add_i32 s59, 0, 0x10000
	s_add_i32 s60, 0, 0x14000
	s_sext_i32_i16 s21, s6
	v_mov_b32_e32 v137, v133
	v_lshl_add_u32 v138, v11, 1, v0
	v_mov_b32_e32 v139, v133
	v_mov_b64_e32 v[140:141], 0xb00
	v_mov_b64_e32 v[142:143], 0xaff
	v_add_u32_e32 v163, s59, v162
	v_add_u32_e32 v164, s60, v162
	v_add_u32_e32 v165, 0, v2
	v_mov_b32_e32 v166, 0x358637bd
	s_movk_i32 s61, 0x1600
	s_lshl_b32 s20, s20, 1
	s_mov_b32 s6, s7
	s_barrier
	s_branch .LBB0_781

.LBB0_783:
	s_ashr_i32 s23, s22, 31
	s_lshl_b64 s[26:27], s[22:23], 19
	s_add_u32 s26, s43, s26
	s_addc_u32 s27, s44, s27
	s_and_b64 s[28:29], s[4:5], exec
	s_cselect_b32 s23, s27, s37
	s_cselect_b32 s31, s26, s36
	s_ashr_i32 s25, s24, 31
	s_lshl_b64 s[28:29], s[24:25], 19
	s_add_u32 s28, s45, s28
	s_addc_u32 s29, s46, s29
	s_and_b64 s[40:41], s[4:5], exec
	s_cselect_b32 s25, s29, s39
	s_cselect_b32 s62, s28, s38
	s_add_u32 s36, s36, 0x40080
	s_addc_u32 s37, s37, 0
	s_add_u32 s63, s38, 0x100
	s_addc_u32 s64, s39, 0
	s_mov_b32 s65, -2
	ds_read_b128 v[144:147], v163
	ds_read_b128 v[148:151], v163 offset:1024
	ds_read_b128 v[152:155], v163 offset:2048
	ds_read_b128 v[156:159], v163 offset:3072
	ds_read_b128 v[168:171], v164
	ds_read_b128 v[172:175], v164 offset:1024
	ds_read_b128 v[176:179], v164 offset:2048
	ds_read_b128 v[180:183], v164 offset:3072
	s_add_u32 s38, s36, 0xfffc0080
	s_addc_u32 s39, s37, -1
	s_cmp_eq_u32 s65, 12
	s_cselect_b32 s41, s23, s39
	s_cselect_b32 s40, s31, s38
	s_cselect_b32 s39, s25, s64
	s_cselect_b32 s38, s62, s63
	v_lshl_add_u64 v[160:161], s[36:37], 0, v[136:137]
	s_add_i32 m0, s50, 0xc000
	ds_read_b128 v[184:187], v165
	ds_read_b128 v[188:191], v165 offset:1024
	ds_read_b128 v[192:195], v165 offset:2048
	ds_read_b128 v[196:199], v165 offset:3072
	ds_read_b128 v[200:203], v165 offset:4096
	ds_read_b128 v[204:207], v165 offset:5120
	ds_read_b128 v[208:211], v165 offset:6144
	ds_read_b128 v[212:215], v165 offset:7168
	global_load_lds_dwordx4 v[160:161], off
	s_add_i32 m0, s50, 0xe000
	v_lshl_add_u64 v[160:161], s[36:37], 0, v[138:139]
	global_load_lds_dwordx4 v[160:161], off
	s_waitcnt lgkmcnt(0)
	s_barrier
	s_setprio 1
	v_mfma_f32_16x16x32_bf16 v[124:127], v[144:147], v[184:187], 0
	v_mfma_f32_16x16x32_bf16 v[120:123], v[152:155], v[184:187], 0
	v_mfma_f32_16x16x32_bf16 v[108:111], v[144:147], v[192:195], 0
	v_mfma_f32_16x16x32_bf16 v[104:107], v[152:155], v[192:195], 0
	v_mfma_f32_16x16x32_bf16 v[92:95], v[144:147], v[200:203], 0
	v_mfma_f32_16x16x32_bf16 v[88:91], v[152:155], v[200:203], 0
	v_mfma_f32_16x16x32_bf16 v[76:79], v[144:147], v[208:211], 0
	v_mfma_f32_16x16x32_bf16 v[72:75], v[152:155], v[208:211], 0
	v_mfma_f32_16x16x32_bf16 v[124:127], v[148:151], v[188:191], v[124:127]
	v_mfma_f32_16x16x32_bf16 v[120:123], v[156:159], v[188:191], v[120:123]
	v_mfma_f32_16x16x32_bf16 v[108:111], v[148:151], v[196:199], v[108:111]
	v_mfma_f32_16x16x32_bf16 v[104:107], v[156:159], v[196:199], v[104:107]
	v_mfma_f32_16x16x32_bf16 v[92:95], v[148:151], v[204:207], v[92:95]
	v_mfma_f32_16x16x32_bf16 v[88:91], v[156:159], v[204:207], v[88:91]
	v_mfma_f32_16x16x32_bf16 v[76:79], v[148:151], v[212:215], v[76:79]
	v_mfma_f32_16x16x32_bf16 v[72:75], v[156:159], v[212:215], v[72:75]
	v_mfma_f32_16x16x32_bf16 v[116:119], v[168:171], v[184:187], 0
	v_mfma_f32_16x16x32_bf16 v[112:115], v[176:179], v[184:187], 0
	v_mfma_f32_16x16x32_bf16 v[100:103], v[168:171], v[192:195], 0
	v_mfma_f32_16x16x32_bf16 v[96:99], v[176:179], v[192:195], 0
	v_mfma_f32_16x16x32_bf16 v[84:87], v[168:171], v[200:203], 0
	v_mfma_f32_16x16x32_bf16 v[80:83], v[176:179], v[200:203], 0
	v_mfma_f32_16x16x32_bf16 v[68:71], v[168:171], v[208:211], 0
	v_mfma_f32_16x16x32_bf16 v[64:67], v[176:179], v[208:211], 0
	v_mfma_f32_16x16x32_bf16 v[116:119], v[172:175], v[188:191], v[116:119]
	v_mfma_f32_16x16x32_bf16 v[112:115], v[180:183], v[188:191], v[112:115]
	v_mfma_f32_16x16x32_bf16 v[100:103], v[172:175], v[196:199], v[100:103]
	v_mfma_f32_16x16x32_bf16 v[96:99], v[180:183], v[196:199], v[96:99]
	s_setprio 2
	s_barrier
	v_mfma_f32_16x16x32_bf16 v[84:87], v[172:175], v[204:207], v[84:87]
	v_mfma_f32_16x16x32_bf16 v[80:83], v[180:183], v[204:207], v[80:83]
	v_mfma_f32_16x16x32_bf16 v[68:71], v[172:175], v[212:215], v[68:71]
	v_mfma_f32_16x16x32_bf16 v[64:67], v[180:183], v[212:215], v[64:67]
	s_setprio 2
	s_add_i32 s66, s59, s47
	v_lshl_add_u64 v[160:161], s[38:39], 0, v[132:133]
	s_mov_b32 m0, s66
	ds_read_b128 v[184:187], v165 offset:16384
	ds_read_b128 v[188:191], v165 offset:17408
	ds_read_b128 v[192:195], v165 offset:18432
	ds_read_b128 v[196:199], v165 offset:19456
	ds_read_b128 v[200:203], v165 offset:20480
	ds_read_b128 v[204:207], v165 offset:21504
	ds_read_b128 v[208:211], v165 offset:22528
	ds_read_b128 v[212:215], v165 offset:23552
	global_load_lds_dwordx4 v[160:161], off
	s_add_i32 m0, s66, 0x2000
	s_add_u32 s66, s38, 0x40000
	v_lshl_add_u64 v[216:217], s[38:39], 0, v[128:129]
	s_addc_u32 s67, s39, 0
	s_add_i32 s68, s60, s47
	global_load_lds_dwordx4 v[216:217], off
	v_lshl_add_u64 v[218:219], s[66:67], 0, v[132:133]
	s_mov_b32 m0, s68
	v_lshl_add_u64 v[220:221], s[40:41], 0, v[130:131]
	global_load_lds_dwordx4 v[218:219], off
	s_add_i32 m0, s68, 0x2000
	v_lshl_add_u64 v[218:219], s[66:67], 0, v[128:129]
	global_load_lds_dwordx4 v[218:219], off
	s_mov_b32 m0, s50
	v_lshl_add_u64 v[218:219], s[40:41], 0, v[134:135]
	global_load_lds_dwordx4 v[218:219], off
	s_mov_b32 m0, s51
	s_nop 0
	global_load_lds_dwordx4 v[220:221], off
	s_waitcnt lgkmcnt(0)
	s_barrier
	s_setprio 1
	v_mfma_f32_16x16x32_bf16 v[60:63], v[144:147], v[184:187], 0
	v_mfma_f32_16x16x32_bf16 v[56:59], v[152:155], v[184:187], 0
	v_mfma_f32_16x16x32_bf16 v[44:47], v[144:147], v[192:195], 0
	v_mfma_f32_16x16x32_bf16 v[40:43], v[152:155], v[192:195], 0
	v_mfma_f32_16x16x32_bf16 v[28:31], v[144:147], v[200:203], 0
	v_mfma_f32_16x16x32_bf16 v[24:27], v[152:155], v[200:203], 0
	v_mfma_f32_16x16x32_bf16 v[12:15], v[144:147], v[208:211], 0
	v_mfma_f32_16x16x32_bf16 v[8:11], v[152:155], v[208:211], 0
	v_mfma_f32_16x16x32_bf16 v[60:63], v[148:151], v[188:191], v[60:63]
	v_mfma_f32_16x16x32_bf16 v[56:59], v[156:159], v[188:191], v[56:59]
	v_mfma_f32_16x16x32_bf16 v[44:47], v[148:151], v[196:199], v[44:47]
	v_mfma_f32_16x16x32_bf16 v[40:43], v[156:159], v[196:199], v[40:43]
	v_mfma_f32_16x16x32_bf16 v[28:31], v[148:151], v[204:207], v[28:31]
	v_mfma_f32_16x16x32_bf16 v[24:27], v[156:159], v[204:207], v[24:27]
	v_mfma_f32_16x16x32_bf16 v[12:15], v[148:151], v[212:215], v[12:15]
	v_mfma_f32_16x16x32_bf16 v[8:11], v[156:159], v[212:215], v[8:11]
	v_mfma_f32_16x16x32_bf16 v[52:55], v[168:171], v[184:187], 0
	v_mfma_f32_16x16x32_bf16 v[48:51], v[176:179], v[184:187], 0
	v_mfma_f32_16x16x32_bf16 v[36:39], v[168:171], v[192:195], 0
	v_mfma_f32_16x16x32_bf16 v[32:35], v[176:179], v[192:195], 0
	v_mfma_f32_16x16x32_bf16 v[20:23], v[168:171], v[200:203], 0
	v_mfma_f32_16x16x32_bf16 v[16:19], v[176:179], v[200:203], 0
	v_mfma_f32_16x16x32_bf16 v[4:7], v[168:171], v[208:211], 0
	v_mfma_f32_16x16x32_bf16 v[0:3], v[176:179], v[208:211], 0
	v_mfma_f32_16x16x32_bf16 v[52:55], v[172:175], v[188:191], v[52:55]
	v_mfma_f32_16x16x32_bf16 v[48:51], v[180:183], v[188:191], v[48:51]
	v_mfma_f32_16x16x32_bf16 v[36:39], v[172:175], v[196:199], v[36:39]
	v_mfma_f32_16x16x32_bf16 v[32:35], v[180:183], v[196:199], v[32:35]
	s_setprio 2
	s_barrier
	v_mfma_f32_16x16x32_bf16 v[20:23], v[172:175], v[204:207], v[20:23]
	v_mfma_f32_16x16x32_bf16 v[16:19], v[180:183], v[204:207], v[16:19]
	v_mfma_f32_16x16x32_bf16 v[4:7], v[172:175], v[212:215], v[4:7]
	v_mfma_f32_16x16x32_bf16 v[0:3], v[180:183], v[212:215], v[0:3]
	s_setprio 0
	s_add_i32 s66, 0, 0x18000
	s_add_i32 s67, 0, 0x1c000
	v_add_u32_e32 v156, s66, v162
	v_add_u32_e32 v167, s67, v162
	ds_read_b128 v[144:147], v156
	ds_read_b128 v[148:151], v156 offset:1024
	ds_read_b128 v[152:155], v156 offset:2048
	ds_read_b128 v[156:159], v156 offset:3072
	ds_read_b128 v[168:171], v167
	ds_read_b128 v[172:175], v167 offset:1024
	ds_read_b128 v[176:179], v167 offset:2048
	ds_read_b128 v[180:183], v167 offset:3072
	s_add_u32 s40, s40, 0x40000
	s_addc_u32 s41, s41, 0
	s_mov_b32 m0, s54
	v_lshl_add_u64 v[222:223], s[40:41], 0, v[134:135]
	ds_read_b128 v[184:187], v165 offset:32768
	ds_read_b128 v[188:191], v165 offset:33792
	ds_read_b128 v[192:195], v165 offset:34816
	ds_read_b128 v[196:199], v165 offset:35840
	ds_read_b128 v[200:203], v165 offset:36864
	ds_read_b128 v[204:207], v165 offset:37888
	ds_read_b128 v[208:211], v165 offset:38912
	ds_read_b128 v[212:215], v165 offset:39936
	global_load_lds_dwordx4 v[222:223], off
	s_mov_b32 m0, s55
	v_lshl_add_u64 v[222:223], s[40:41], 0, v[130:131]
	global_load_lds_dwordx4 v[222:223], off
	s_waitcnt vmcnt(8) lgkmcnt(0)
	s_barrier
	s_setprio 1
	v_mfma_f32_16x16x32_bf16 v[124:127], v[144:147], v[184:187], v[124:127]
	v_mfma_f32_16x16x32_bf16 v[120:123], v[152:155], v[184:187], v[120:123]
	v_mfma_f32_16x16x32_bf16 v[108:111], v[144:147], v[192:195], v[108:111]
	v_mfma_f32_16x16x32_bf16 v[104:107], v[152:155], v[192:195], v[104:107]
	v_mfma_f32_16x16x32_bf16 v[92:95], v[144:147], v[200:203], v[92:95]
	v_mfma_f32_16x16x32_bf16 v[88:91], v[152:155], v[200:203], v[88:91]
	v_mfma_f32_16x16x32_bf16 v[76:79], v[144:147], v[208:211], v[76:79]
	v_mfma_f32_16x16x32_bf16 v[72:75], v[152:155], v[208:211], v[72:75]
	v_mfma_f32_16x16x32_bf16 v[124:127], v[148:151], v[188:191], v[124:127]
	v_mfma_f32_16x16x32_bf16 v[120:123], v[156:159], v[188:191], v[120:123]
	v_mfma_f32_16x16x32_bf16 v[108:111], v[148:151], v[196:199], v[108:111]
	v_mfma_f32_16x16x32_bf16 v[104:107], v[156:159], v[196:199], v[104:107]
	v_mfma_f32_16x16x32_bf16 v[92:95], v[148:151], v[204:207], v[92:95]
	v_mfma_f32_16x16x32_bf16 v[88:91], v[156:159], v[204:207], v[88:91]
	v_mfma_f32_16x16x32_bf16 v[76:79], v[148:151], v[212:215], v[76:79]
	v_mfma_f32_16x16x32_bf16 v[72:75], v[156:159], v[212:215], v[72:75]
	v_mfma_f32_16x16x32_bf16 v[116:119], v[168:171], v[184:187], v[116:119]
	v_mfma_f32_16x16x32_bf16 v[112:115], v[176:179], v[184:187], v[112:115]
	v_mfma_f32_16x16x32_bf16 v[100:103], v[168:171], v[192:195], v[100:103]
	v_mfma_f32_16x16x32_bf16 v[96:99], v[176:179], v[192:195], v[96:99]
	v_mfma_f32_16x16x32_bf16 v[84:87], v[168:171], v[200:203], v[84:87]
	v_mfma_f32_16x16x32_bf16 v[80:83], v[176:179], v[200:203], v[80:83]
	v_mfma_f32_16x16x32_bf16 v[68:71], v[168:171], v[208:211], v[68:71]
	v_mfma_f32_16x16x32_bf16 v[64:67], v[176:179], v[208:211], v[64:67]
	v_mfma_f32_16x16x32_bf16 v[116:119], v[172:175], v[188:191], v[116:119]
	v_mfma_f32_16x16x32_bf16 v[112:115], v[180:183], v[188:191], v[112:115]
	v_mfma_f32_16x16x32_bf16 v[100:103], v[172:175], v[196:199], v[100:103]
	v_mfma_f32_16x16x32_bf16 v[96:99], v[180:183], v[196:199], v[96:99]
	s_setprio 2
	s_barrier
	v_mfma_f32_16x16x32_bf16 v[84:87], v[172:175], v[204:207], v[84:87]
	v_mfma_f32_16x16x32_bf16 v[80:83], v[180:183], v[204:207], v[80:83]
	v_mfma_f32_16x16x32_bf16 v[68:71], v[172:175], v[212:215], v[68:71]
	v_mfma_f32_16x16x32_bf16 v[64:67], v[180:183], v[212:215], v[64:67]
	s_setprio 2
	s_add_i32 s40, s66, s47
	v_lshl_add_u64 v[160:161], v[160:161], 0, s[16:17]
	s_mov_b32 m0, s40
	ds_read_b128 v[184:187], v165 offset:49152
	ds_read_b128 v[188:191], v165 offset:50176
	ds_read_b128 v[192:195], v165 offset:51200
	ds_read_b128 v[196:199], v165 offset:52224
	ds_read_b128 v[200:203], v165 offset:53248
	ds_read_b128 v[204:207], v165 offset:54272
	ds_read_b128 v[208:211], v165 offset:55296
	ds_read_b128 v[212:215], v165 offset:56320
	global_load_lds_dwordx4 v[160:161], off
	s_add_i32 m0, s40, 0x2000
	s_add_u32 s38, s38, 0x40080
	v_lshl_add_u64 v[160:161], v[216:217], 0, s[16:17]
	s_addc_u32 s39, s39, 0
	s_add_i32 s40, s67, s47
	global_load_lds_dwordx4 v[160:161], off
	s_mov_b32 m0, s40
	v_lshl_add_u64 v[160:161], s[38:39], 0, v[132:133]
	global_load_lds_dwordx4 v[160:161], off
	s_add_i32 m0, s40, 0x2000
	v_lshl_add_u64 v[160:161], s[38:39], 0, v[128:129]
	global_load_lds_dwordx4 v[160:161], off
	s_mov_b32 m0, s57
	v_lshl_add_u64 v[160:161], v[218:219], 0, s[16:17]
	global_load_lds_dwordx4 v[160:161], off
	s_mov_b32 m0, s58
	v_lshl_add_u64 v[160:161], v[220:221], 0, s[16:17]
	global_load_lds_dwordx4 v[160:161], off
	s_waitcnt vmcnt(8) lgkmcnt(0)
	s_barrier
	s_setprio 1
	v_mfma_f32_16x16x32_bf16 v[60:63], v[144:147], v[184:187], v[60:63]
	v_mfma_f32_16x16x32_bf16 v[56:59], v[152:155], v[184:187], v[56:59]
	v_mfma_f32_16x16x32_bf16 v[44:47], v[144:147], v[192:195], v[44:47]
	v_mfma_f32_16x16x32_bf16 v[40:43], v[152:155], v[192:195], v[40:43]
	v_mfma_f32_16x16x32_bf16 v[28:31], v[144:147], v[200:203], v[28:31]
	v_mfma_f32_16x16x32_bf16 v[24:27], v[152:155], v[200:203], v[24:27]
	v_mfma_f32_16x16x32_bf16 v[12:15], v[144:147], v[208:211], v[12:15]
	v_mfma_f32_16x16x32_bf16 v[8:11], v[152:155], v[208:211], v[8:11]
	v_mfma_f32_16x16x32_bf16 v[60:63], v[148:151], v[188:191], v[60:63]
	v_mfma_f32_16x16x32_bf16 v[56:59], v[156:159], v[188:191], v[56:59]
	v_mfma_f32_16x16x32_bf16 v[44:47], v[148:151], v[196:199], v[44:47]
	v_mfma_f32_16x16x32_bf16 v[40:43], v[156:159], v[196:199], v[40:43]
	v_mfma_f32_16x16x32_bf16 v[28:31], v[148:151], v[204:207], v[28:31]
	v_mfma_f32_16x16x32_bf16 v[24:27], v[156:159], v[204:207], v[24:27]
	v_mfma_f32_16x16x32_bf16 v[12:15], v[148:151], v[212:215], v[12:15]
	v_mfma_f32_16x16x32_bf16 v[8:11], v[156:159], v[212:215], v[8:11]
	v_mfma_f32_16x16x32_bf16 v[52:55], v[168:171], v[184:187], v[52:55]
	v_mfma_f32_16x16x32_bf16 v[48:51], v[176:179], v[184:187], v[48:51]
	v_mfma_f32_16x16x32_bf16 v[36:39], v[168:171], v[192:195], v[36:39]
	v_mfma_f32_16x16x32_bf16 v[32:35], v[176:179], v[192:195], v[32:35]
	v_mfma_f32_16x16x32_bf16 v[20:23], v[168:171], v[200:203], v[20:23]
	v_mfma_f32_16x16x32_bf16 v[16:19], v[176:179], v[200:203], v[16:19]
	v_mfma_f32_16x16x32_bf16 v[4:7], v[168:171], v[208:211], v[4:7]
	v_mfma_f32_16x16x32_bf16 v[0:3], v[176:179], v[208:211], v[0:3]
	v_mfma_f32_16x16x32_bf16 v[52:55], v[172:175], v[188:191], v[52:55]
	v_mfma_f32_16x16x32_bf16 v[48:51], v[180:183], v[188:191], v[48:51]
	v_mfma_f32_16x16x32_bf16 v[36:39], v[172:175], v[196:199], v[36:39]
	v_mfma_f32_16x16x32_bf16 v[32:35], v[180:183], v[196:199], v[32:35]
	s_setprio 2
	s_barrier
	v_mfma_f32_16x16x32_bf16 v[20:23], v[172:175], v[204:207], v[20:23]
	v_mfma_f32_16x16x32_bf16 v[16:19], v[180:183], v[204:207], v[16:19]
	v_mfma_f32_16x16x32_bf16 v[4:7], v[172:175], v[212:215], v[4:7]
	v_mfma_f32_16x16x32_bf16 v[0:3], v[180:183], v[212:215], v[0:3]
	s_setprio 0
	s_add_i32 s65, s65, 2
	s_add_u32 s36, s36, 0x100
	s_addc_u32 s37, s37, 0
	s_add_u32 s63, s63, 0x100
	s_addc_u32 s64, s64, 0
	s_cmp_gt_u32 s65, 13

.LBB0_852:
	s_add_u32 s14, s4, 0x14800000
	s_addc_u32 s15, s5, 0
	s_add_u32 s16, s4, 0x120000
	s_addc_u32 s17, s5, 0
	s_lshl_b32 s7, s7, 5
	s_mov_b64 s[20:21], 0x80
	s_and_b32 s18, s7, 0x60
	s_add_i32 m0, s44, 0x18000
	v_lshl_add_u64 v[6:7], v[6:7], 0, s[20:21]
	s_lshl_b32 s48, s8, 6
	s_lshl_b32 s8, s8, 13
	s_lshl_b32 s7, s18, 7
	s_waitcnt vmcnt(2)
	s_barrier
	global_load_lds_dwordx4 v[6:7], off
	v_lshl_add_u64 v[4:5], v[4:5], 0, s[20:21]
	s_add_i32 m0, s44, 0x1a000
	s_add_i32 s49, s44, 0x8000
	s_add_i32 s50, s44, 0xa000
	global_load_lds_dwordx4 v[4:5], off
	v_lshl_add_u64 v[0:1], v[0:1], 0, s[20:21]
	s_mov_b32 m0, s49
	s_add_u32 s22, s28, 0xb0080
	global_load_lds_dwordx4 v[0:1], off
	v_lshl_add_u64 v[0:1], v[2:3], 0, s[20:21]
	s_mov_b32 m0, s50
	s_addc_u32 s23, s29, 0
	global_load_lds_dwordx4 v[0:1], off
	s_add_i32 m0, s44, 0x1c000
	v_lshl_add_u64 v[0:1], s[22:23], 0, v[186:187]
	global_load_lds_dwordx4 v[0:1], off
	v_lshl_add_u64 v[0:1], s[22:23], 0, v[190:191]
	s_add_i32 m0, s44, 0x1e000
	s_movk_i32 s22, 0x3c0
	global_load_lds_dwordx4 v[0:1], off
	v_and_b32_e32 v0, 48, v8
	v_lshlrev_b32_e32 v1, 6, v8
	v_and_or_b32 v0, v1, s22, v0
	v_lshlrev_b32_e32 v1, 2, v8
	v_and_b32_e32 v1, 32, v1
	s_cmpk_lt_u32 s19, 0x100
	v_bitop3_b32 v232, s7, v0, v1 bitop3:0xf6
	s_cselect_b64 s[22:23], -1, 0
	s_ashr_i32 s51, s38, 31
	s_lshl_b32 s7, s18, 1
	s_add_u32 s4, s4, s7
	s_addc_u32 s5, s5, 0
	v_bitop3_b32 v2, v0, s8, v1 bitop3:0xde
	s_add_u32 s54, s4, 0xf800000
	v_lshrrev_b32_e32 v1, 1, v9
	v_mul_lo_u32 v0, v11, s6
	s_mov_b32 s7, 0xb000
	s_addc_u32 s55, s5, 0
	v_mad_u64_u32 v[0:1], s[4:5], v1, s7, v[0:1]
	v_or_b32_e32 v0, v0, v10
	s_mov_b64 s[24:25], 0xb0080
	v_add_lshl_u32 v0, v0, v12, 1
	v_mov_b32_e32 v1, v187
	v_lshl_add_u64 v[192:193], v[0:1], 0, s[24:25]
	v_lshrrev_b32_e32 v1, 1, v13
	v_mul_lo_u32 v0, v14, s6
	v_mad_u64_u32 v[0:1], s[4:5], v1, s7, v[0:1]
	s_waitcnt vmcnt(0)
	v_or_b32_e32 v0, v0, v15
	v_add_lshl_u32 v0, v0, v16, 1
	v_mov_b32_e32 v1, v187
	s_add_i32 s56, 0, 0x10000
	s_add_i32 s57, 0, 0x14000
	s_mov_b32 s19, s9
	v_lshl_add_u64 v[194:195], v[0:1], 0, s[24:25]
	v_mov_b64_e32 v[196:197], 0x200
	v_mov_b64_e32 v[198:199], 0x1ff
	v_add_u32_e32 v233, s56, v232
	v_add_u32_e32 v234, s57, v232
	v_add_u32_e32 v235, 0, v2
	s_mov_b32 s8, s9
	s_barrier
	s_branch .LBB0_855

.LBB0_865:
	s_add_u32 s62, s28, 0x100
	s_addc_u32 s63, s29, 0
	s_mov_b32 s64, -2
	ds_read_b128 v[120:123], v233
	ds_read_b128 v[124:127], v233 offset:1024
	ds_read_b128 v[136:139], v233 offset:2048
	ds_read_b128 v[140:143], v233 offset:3072
	ds_read_b128 v[144:147], v234
	ds_read_b128 v[148:151], v234 offset:1024
	ds_read_b128 v[152:155], v234 offset:2048
	ds_read_b128 v[156:159], v234 offset:3072
	s_add_u32 s28, s26, 0x100
	s_addc_u32 s29, s27, 0
	s_cmp_eq_u32 s64, 40
	s_cselect_b32 s37, s7, s29
	s_cselect_b32 s36, s6, s28
	s_cselect_b32 s31, s25, s63
	s_cselect_b32 s30, s24, s62
	v_lshl_add_u64 v[208:209], s[26:27], 0, v[192:193]
	s_add_i32 m0, s44, 0xc000
	ds_read_b128 v[160:163], v235
	ds_read_b128 v[164:167], v235 offset:1024
	ds_read_b128 v[168:171], v235 offset:2048
	ds_read_b128 v[172:175], v235 offset:3072
	ds_read_b128 v[176:179], v235 offset:4096
	ds_read_b128 v[180:183], v235 offset:5120
	ds_read_b128 v[200:203], v235 offset:6144
	ds_read_b128 v[204:207], v235 offset:7168
	global_load_lds_dwordx4 v[208:209], off
	s_add_i32 m0, s44, 0xe000
	v_lshl_add_u64 v[208:209], s[26:27], 0, v[194:195]
	global_load_lds_dwordx4 v[208:209], off
	s_waitcnt lgkmcnt(0)
	s_barrier
	s_setprio 1
	v_mfma_f32_16x16x32_bf16 v[132:135], v[120:123], v[160:163], 0
	v_mfma_f32_16x16x32_bf16 v[128:131], v[136:139], v[160:163], 0
	v_mfma_f32_16x16x32_bf16 v[108:111], v[120:123], v[168:171], 0
	v_mfma_f32_16x16x32_bf16 v[104:107], v[136:139], v[168:171], 0
	v_mfma_f32_16x16x32_bf16 v[92:95], v[120:123], v[176:179], 0
	v_mfma_f32_16x16x32_bf16 v[88:91], v[136:139], v[176:179], 0
	v_mfma_f32_16x16x32_bf16 v[76:79], v[120:123], v[200:203], 0
	v_mfma_f32_16x16x32_bf16 v[72:75], v[136:139], v[200:203], 0
	v_mfma_f32_16x16x32_bf16 v[132:135], v[124:127], v[164:167], v[132:135]
	v_mfma_f32_16x16x32_bf16 v[128:131], v[140:143], v[164:167], v[128:131]
	v_mfma_f32_16x16x32_bf16 v[108:111], v[124:127], v[172:175], v[108:111]
	v_mfma_f32_16x16x32_bf16 v[104:107], v[140:143], v[172:175], v[104:107]
	v_mfma_f32_16x16x32_bf16 v[92:95], v[124:127], v[180:183], v[92:95]
	v_mfma_f32_16x16x32_bf16 v[88:91], v[140:143], v[180:183], v[88:91]
	v_mfma_f32_16x16x32_bf16 v[76:79], v[124:127], v[204:207], v[76:79]
	v_mfma_f32_16x16x32_bf16 v[72:75], v[140:143], v[204:207], v[72:75]
	v_mfma_f32_16x16x32_bf16 v[116:119], v[144:147], v[160:163], 0
	v_mfma_f32_16x16x32_bf16 v[112:115], v[152:155], v[160:163], 0
	v_mfma_f32_16x16x32_bf16 v[100:103], v[144:147], v[168:171], 0
	v_mfma_f32_16x16x32_bf16 v[96:99], v[152:155], v[168:171], 0
	v_mfma_f32_16x16x32_bf16 v[84:87], v[144:147], v[176:179], 0
	v_mfma_f32_16x16x32_bf16 v[80:83], v[152:155], v[176:179], 0
	v_mfma_f32_16x16x32_bf16 v[68:71], v[144:147], v[200:203], 0
	v_mfma_f32_16x16x32_bf16 v[64:67], v[152:155], v[200:203], 0
	v_mfma_f32_16x16x32_bf16 v[116:119], v[148:151], v[164:167], v[116:119]
	v_mfma_f32_16x16x32_bf16 v[112:115], v[156:159], v[164:167], v[112:115]
	v_mfma_f32_16x16x32_bf16 v[100:103], v[148:151], v[172:175], v[100:103]
	v_mfma_f32_16x16x32_bf16 v[96:99], v[156:159], v[172:175], v[96:99]
	s_setprio 2
	s_barrier
	v_mfma_f32_16x16x32_bf16 v[84:87], v[148:151], v[180:183], v[84:87]
	v_mfma_f32_16x16x32_bf16 v[80:83], v[156:159], v[180:183], v[80:83]
	v_mfma_f32_16x16x32_bf16 v[68:71], v[148:151], v[204:207], v[68:71]
	v_mfma_f32_16x16x32_bf16 v[64:67], v[156:159], v[204:207], v[64:67]
	s_setprio 2
	s_add_i32 s26, s56, s43
	v_lshl_add_u64 v[208:209], s[30:31], 0, v[186:187]
	s_mov_b32 m0, s26
	ds_read_b128 v[160:163], v235 offset:16384
	ds_read_b128 v[164:167], v235 offset:17408
	ds_read_b128 v[168:171], v235 offset:18432
	ds_read_b128 v[172:175], v235 offset:19456
	ds_read_b128 v[176:179], v235 offset:20480
	ds_read_b128 v[180:183], v235 offset:21504
	ds_read_b128 v[200:203], v235 offset:22528
	ds_read_b128 v[204:207], v235 offset:23552
	global_load_lds_dwordx4 v[208:209], off
	s_add_i32 m0, s26, 0x2000
	s_add_u32 s26, s30, 0xb0000
	v_lshl_add_u64 v[210:211], s[30:31], 0, v[190:191]
	s_addc_u32 s27, s31, 0
	s_add_i32 s65, s57, s43
	global_load_lds_dwordx4 v[210:211], off
	v_lshl_add_u64 v[212:213], s[26:27], 0, v[186:187]
	s_mov_b32 m0, s65
	v_lshl_add_u64 v[214:215], s[36:37], 0, v[188:189]
	global_load_lds_dwordx4 v[212:213], off
	s_add_i32 m0, s65, 0x2000
	v_lshl_add_u64 v[212:213], s[26:27], 0, v[190:191]
	global_load_lds_dwordx4 v[212:213], off
	s_mov_b32 m0, s44
	v_lshl_add_u64 v[212:213], s[36:37], 0, v[184:185]
	global_load_lds_dwordx4 v[212:213], off
	s_mov_b32 m0, s45
	s_nop 0
	global_load_lds_dwordx4 v[214:215], off
	s_waitcnt lgkmcnt(0)
	s_barrier
	s_setprio 1
	v_mfma_f32_16x16x32_bf16 v[60:63], v[120:123], v[160:163], 0
	v_mfma_f32_16x16x32_bf16 v[56:59], v[136:139], v[160:163], 0
	v_mfma_f32_16x16x32_bf16 v[44:47], v[120:123], v[168:171], 0
	v_mfma_f32_16x16x32_bf16 v[40:43], v[136:139], v[168:171], 0
	v_mfma_f32_16x16x32_bf16 v[28:31], v[120:123], v[176:179], 0
	v_mfma_f32_16x16x32_bf16 v[24:27], v[136:139], v[176:179], 0
	v_mfma_f32_16x16x32_bf16 v[12:15], v[120:123], v[200:203], 0
	v_mfma_f32_16x16x32_bf16 v[8:11], v[136:139], v[200:203], 0
	v_mfma_f32_16x16x32_bf16 v[60:63], v[124:127], v[164:167], v[60:63]
	v_mfma_f32_16x16x32_bf16 v[56:59], v[140:143], v[164:167], v[56:59]
	v_mfma_f32_16x16x32_bf16 v[44:47], v[124:127], v[172:175], v[44:47]
	v_mfma_f32_16x16x32_bf16 v[40:43], v[140:143], v[172:175], v[40:43]
	v_mfma_f32_16x16x32_bf16 v[28:31], v[124:127], v[180:183], v[28:31]
	v_mfma_f32_16x16x32_bf16 v[24:27], v[140:143], v[180:183], v[24:27]
	v_mfma_f32_16x16x32_bf16 v[12:15], v[124:127], v[204:207], v[12:15]
	v_mfma_f32_16x16x32_bf16 v[8:11], v[140:143], v[204:207], v[8:11]
	v_mfma_f32_16x16x32_bf16 v[52:55], v[144:147], v[160:163], 0
	v_mfma_f32_16x16x32_bf16 v[48:51], v[152:155], v[160:163], 0
	v_mfma_f32_16x16x32_bf16 v[36:39], v[144:147], v[168:171], 0
	v_mfma_f32_16x16x32_bf16 v[32:35], v[152:155], v[168:171], 0
	v_mfma_f32_16x16x32_bf16 v[20:23], v[144:147], v[176:179], 0
	v_mfma_f32_16x16x32_bf16 v[16:19], v[152:155], v[176:179], 0
	v_mfma_f32_16x16x32_bf16 v[4:7], v[144:147], v[200:203], 0
	v_mfma_f32_16x16x32_bf16 v[0:3], v[152:155], v[200:203], 0
	v_mfma_f32_16x16x32_bf16 v[52:55], v[148:151], v[164:167], v[52:55]
	v_mfma_f32_16x16x32_bf16 v[48:51], v[156:159], v[164:167], v[48:51]
	v_mfma_f32_16x16x32_bf16 v[36:39], v[148:151], v[172:175], v[36:39]
	v_mfma_f32_16x16x32_bf16 v[32:35], v[156:159], v[172:175], v[32:35]
	s_setprio 2
	s_barrier
	v_mfma_f32_16x16x32_bf16 v[20:23], v[148:151], v[180:183], v[20:23]
	v_mfma_f32_16x16x32_bf16 v[16:19], v[156:159], v[180:183], v[16:19]
	v_mfma_f32_16x16x32_bf16 v[4:7], v[148:151], v[204:207], v[4:7]
	v_mfma_f32_16x16x32_bf16 v[0:3], v[156:159], v[204:207], v[0:3]
	s_setprio 0
	s_add_i32 s65, 0, 0x18000
	s_add_i32 s66, 0, 0x1c000
	v_add_u32_e32 v140, s65, v232
	v_add_u32_e32 v156, s66, v232
	ds_read_b128 v[120:123], v140
	ds_read_b128 v[124:127], v140 offset:1024
	ds_read_b128 v[136:139], v140 offset:2048
	ds_read_b128 v[140:143], v140 offset:3072
	ds_read_b128 v[144:147], v156
	ds_read_b128 v[148:151], v156 offset:1024
	ds_read_b128 v[152:155], v156 offset:2048
	ds_read_b128 v[156:159], v156 offset:3072
	s_add_u32 s26, s36, 0xb0000
	s_addc_u32 s27, s37, 0
	s_mov_b32 m0, s46
	v_lshl_add_u64 v[216:217], s[26:27], 0, v[184:185]
	ds_read_b128 v[160:163], v235 offset:32768
	ds_read_b128 v[164:167], v235 offset:33792
	ds_read_b128 v[168:171], v235 offset:34816
	ds_read_b128 v[172:175], v235 offset:35840
	ds_read_b128 v[176:179], v235 offset:36864
	ds_read_b128 v[180:183], v235 offset:37888
	ds_read_b128 v[200:203], v235 offset:38912
	ds_read_b128 v[204:207], v235 offset:39936
	global_load_lds_dwordx4 v[216:217], off
	s_mov_b32 m0, s47
	v_lshl_add_u64 v[216:217], s[26:27], 0, v[188:189]
	global_load_lds_dwordx4 v[216:217], off
	s_waitcnt vmcnt(8) lgkmcnt(0)
	s_barrier
	s_setprio 1
	v_mfma_f32_16x16x32_bf16 v[132:135], v[120:123], v[160:163], v[132:135]
	v_mfma_f32_16x16x32_bf16 v[128:131], v[136:139], v[160:163], v[128:131]
	v_mfma_f32_16x16x32_bf16 v[108:111], v[120:123], v[168:171], v[108:111]
	v_mfma_f32_16x16x32_bf16 v[104:107], v[136:139], v[168:171], v[104:107]
	v_mfma_f32_16x16x32_bf16 v[92:95], v[120:123], v[176:179], v[92:95]
	v_mfma_f32_16x16x32_bf16 v[88:91], v[136:139], v[176:179], v[88:91]
	v_mfma_f32_16x16x32_bf16 v[76:79], v[120:123], v[200:203], v[76:79]
	v_mfma_f32_16x16x32_bf16 v[72:75], v[136:139], v[200:203], v[72:75]
	v_mfma_f32_16x16x32_bf16 v[132:135], v[124:127], v[164:167], v[132:135]
	v_mfma_f32_16x16x32_bf16 v[128:131], v[140:143], v[164:167], v[128:131]
	v_mfma_f32_16x16x32_bf16 v[108:111], v[124:127], v[172:175], v[108:111]
	v_mfma_f32_16x16x32_bf16 v[104:107], v[140:143], v[172:175], v[104:107]
	v_mfma_f32_16x16x32_bf16 v[92:95], v[124:127], v[180:183], v[92:95]
	v_mfma_f32_16x16x32_bf16 v[88:91], v[140:143], v[180:183], v[88:91]
	v_mfma_f32_16x16x32_bf16 v[76:79], v[124:127], v[204:207], v[76:79]
	v_mfma_f32_16x16x32_bf16 v[72:75], v[140:143], v[204:207], v[72:75]
	v_mfma_f32_16x16x32_bf16 v[116:119], v[144:147], v[160:163], v[116:119]
	v_mfma_f32_16x16x32_bf16 v[112:115], v[152:155], v[160:163], v[112:115]
	v_mfma_f32_16x16x32_bf16 v[100:103], v[144:147], v[168:171], v[100:103]
	v_mfma_f32_16x16x32_bf16 v[96:99], v[152:155], v[168:171], v[96:99]
	v_mfma_f32_16x16x32_bf16 v[84:87], v[144:147], v[176:179], v[84:87]
	v_mfma_f32_16x16x32_bf16 v[80:83], v[152:155], v[176:179], v[80:83]
	v_mfma_f32_16x16x32_bf16 v[68:71], v[144:147], v[200:203], v[68:71]
	v_mfma_f32_16x16x32_bf16 v[64:67], v[152:155], v[200:203], v[64:67]
	v_mfma_f32_16x16x32_bf16 v[116:119], v[148:151], v[164:167], v[116:119]
	v_mfma_f32_16x16x32_bf16 v[112:115], v[156:159], v[164:167], v[112:115]
	v_mfma_f32_16x16x32_bf16 v[100:103], v[148:151], v[172:175], v[100:103]
	v_mfma_f32_16x16x32_bf16 v[96:99], v[156:159], v[172:175], v[96:99]
	s_setprio 2
	s_barrier
	v_mfma_f32_16x16x32_bf16 v[84:87], v[148:151], v[180:183], v[84:87]
	v_mfma_f32_16x16x32_bf16 v[80:83], v[156:159], v[180:183], v[80:83]
	v_mfma_f32_16x16x32_bf16 v[68:71], v[148:151], v[204:207], v[68:71]
	v_mfma_f32_16x16x32_bf16 v[64:67], v[156:159], v[204:207], v[64:67]
	s_setprio 2
	s_add_i32 s26, s65, s43
	v_lshl_add_u64 v[208:209], v[208:209], 0, s[20:21]
	s_mov_b32 m0, s26
	ds_read_b128 v[160:163], v235 offset:49152
	ds_read_b128 v[164:167], v235 offset:50176
	ds_read_b128 v[168:171], v235 offset:51200
	ds_read_b128 v[172:175], v235 offset:52224
	ds_read_b128 v[176:179], v235 offset:53248
	ds_read_b128 v[180:183], v235 offset:54272
	ds_read_b128 v[200:203], v235 offset:55296
	ds_read_b128 v[204:207], v235 offset:56320
	global_load_lds_dwordx4 v[208:209], off
	s_add_i32 m0, s26, 0x2000
	s_add_u32 s26, s30, 0xb0080
	v_lshl_add_u64 v[208:209], v[210:211], 0, s[20:21]
	s_addc_u32 s27, s31, 0
	s_add_i32 s30, s66, s43
	global_load_lds_dwordx4 v[208:209], off
	s_mov_b32 m0, s30
	v_lshl_add_u64 v[208:209], s[26:27], 0, v[186:187]
	global_load_lds_dwordx4 v[208:209], off
	s_add_i32 m0, s30, 0x2000
	v_lshl_add_u64 v[208:209], s[26:27], 0, v[190:191]
	global_load_lds_dwordx4 v[208:209], off
	s_mov_b32 m0, s49
	v_lshl_add_u64 v[208:209], v[212:213], 0, s[20:21]
	global_load_lds_dwordx4 v[208:209], off
	s_mov_b32 m0, s50
	v_lshl_add_u64 v[208:209], v[214:215], 0, s[20:21]
	global_load_lds_dwordx4 v[208:209], off
	s_waitcnt vmcnt(8) lgkmcnt(0)
	s_barrier
	s_setprio 1
	v_mfma_f32_16x16x32_bf16 v[60:63], v[120:123], v[160:163], v[60:63]
	v_mfma_f32_16x16x32_bf16 v[56:59], v[136:139], v[160:163], v[56:59]
	v_mfma_f32_16x16x32_bf16 v[44:47], v[120:123], v[168:171], v[44:47]
	v_mfma_f32_16x16x32_bf16 v[40:43], v[136:139], v[168:171], v[40:43]
	v_mfma_f32_16x16x32_bf16 v[28:31], v[120:123], v[176:179], v[28:31]
	v_mfma_f32_16x16x32_bf16 v[24:27], v[136:139], v[176:179], v[24:27]
	v_mfma_f32_16x16x32_bf16 v[12:15], v[120:123], v[200:203], v[12:15]
	v_mfma_f32_16x16x32_bf16 v[8:11], v[136:139], v[200:203], v[8:11]
	v_mfma_f32_16x16x32_bf16 v[60:63], v[124:127], v[164:167], v[60:63]
	v_mfma_f32_16x16x32_bf16 v[56:59], v[140:143], v[164:167], v[56:59]
	v_mfma_f32_16x16x32_bf16 v[44:47], v[124:127], v[172:175], v[44:47]
	v_mfma_f32_16x16x32_bf16 v[40:43], v[140:143], v[172:175], v[40:43]
	v_mfma_f32_16x16x32_bf16 v[28:31], v[124:127], v[180:183], v[28:31]
	v_mfma_f32_16x16x32_bf16 v[24:27], v[140:143], v[180:183], v[24:27]
	v_mfma_f32_16x16x32_bf16 v[12:15], v[124:127], v[204:207], v[12:15]
	v_mfma_f32_16x16x32_bf16 v[8:11], v[140:143], v[204:207], v[8:11]
	v_mfma_f32_16x16x32_bf16 v[52:55], v[144:147], v[160:163], v[52:55]
	v_mfma_f32_16x16x32_bf16 v[48:51], v[152:155], v[160:163], v[48:51]
	v_mfma_f32_16x16x32_bf16 v[36:39], v[144:147], v[168:171], v[36:39]
	v_mfma_f32_16x16x32_bf16 v[32:35], v[152:155], v[168:171], v[32:35]
	v_mfma_f32_16x16x32_bf16 v[20:23], v[144:147], v[176:179], v[20:23]
	v_mfma_f32_16x16x32_bf16 v[16:19], v[152:155], v[176:179], v[16:19]
	v_mfma_f32_16x16x32_bf16 v[4:7], v[144:147], v[200:203], v[4:7]
	v_mfma_f32_16x16x32_bf16 v[0:3], v[152:155], v[200:203], v[0:3]
	v_mfma_f32_16x16x32_bf16 v[52:55], v[148:151], v[164:167], v[52:55]
	v_mfma_f32_16x16x32_bf16 v[48:51], v[156:159], v[164:167], v[48:51]
	v_mfma_f32_16x16x32_bf16 v[36:39], v[148:151], v[172:175], v[36:39]
	v_mfma_f32_16x16x32_bf16 v[32:35], v[156:159], v[172:175], v[32:35]
	s_setprio 2
	s_barrier
	v_mfma_f32_16x16x32_bf16 v[20:23], v[148:151], v[180:183], v[20:23]
	v_mfma_f32_16x16x32_bf16 v[16:19], v[156:159], v[180:183], v[16:19]
	v_mfma_f32_16x16x32_bf16 v[4:7], v[148:151], v[204:207], v[4:7]
	v_mfma_f32_16x16x32_bf16 v[0:3], v[156:159], v[204:207], v[0:3]
	s_setprio 0
	s_add_i32 s64, s64, 2
	s_add_u32 s62, s62, 0x100
	s_addc_u32 s63, s63, 0
	s_cmp_gt_u32 s64, 41
	s_mov_b64 s[26:27], s[28:29]

.LBB0_946:
	s_add_u32 s18, s22, 0x120000
	s_addc_u32 s19, s23, 0
	s_add_u32 s58, s22, 0x4800000
	s_addc_u32 s59, s23, 0
	s_add_u32 s20, s22, 0x8800000
	s_addc_u32 s21, s23, 0
	s_add_u32 s60, s22, 0xc800000
	s_addc_u32 s61, s23, 0
	s_mov_b64 s[22:23], 0x80
	s_and_b32 s26, s24, 3
	s_add_i32 m0, s54, 0x18000
	v_lshl_add_u64 v[6:7], v[6:7], 0, s[22:23]
	s_lshl_b32 s62, s25, 6
	s_lshl_b32 s24, s25, 13
	s_lshl_b32 s63, s26, 5
	s_lshl_b32 s25, s26, 12
	s_waitcnt vmcnt(2)
	s_barrier
	global_load_lds_dwordx4 v[6:7], off
	v_lshl_add_u64 v[4:5], v[4:5], 0, s[22:23]
	s_add_i32 m0, s54, 0x1a000
	s_add_i32 s64, s54, 0x8000
	s_add_i32 s65, s54, 0xa000
	global_load_lds_dwordx4 v[4:5], off
	v_lshl_add_u64 v[0:1], v[0:1], 0, s[22:23]
	s_mov_b32 m0, s64
	s_add_u32 s4, s40, 0x40080
	global_load_lds_dwordx4 v[0:1], off
	v_lshl_add_u64 v[0:1], v[2:3], 0, s[22:23]
	s_mov_b32 m0, s65
	s_addc_u32 s5, s41, 0
	global_load_lds_dwordx4 v[0:1], off
	s_add_i32 m0, s54, 0x1c000
	v_lshl_add_u64 v[0:1], s[4:5], 0, v[130:131]
	global_load_lds_dwordx4 v[0:1], off
	v_lshl_add_u64 v[0:1], s[4:5], 0, v[134:135]
	s_add_i32 m0, s54, 0x1e000
	s_movk_i32 s4, 0x3c0
	global_load_lds_dwordx4 v[0:1], off
	v_and_b32_e32 v0, 48, v8
	v_lshlrev_b32_e32 v1, 6, v8
	v_and_or_b32 v0, v1, s4, v0
	v_lshlrev_b32_e32 v1, 2, v8
	v_and_b32_e32 v1, 32, v1
	v_bitop3_b32 v2, v0, s24, v1 bitop3:0xde
	v_bitop3_b32 v178, s25, v0, v1 bitop3:0xf6
	v_lshlrev_b32_e32 v0, 14, v9
	v_and_b32_e32 v0, 0xffff8000, v0
	v_lshl_add_u32 v0, v10, 11, v0
	v_and_b32_e32 v1, 1, v9
	v_lshl_or_b32 v0, v1, 6, v0
	v_lshl_add_u32 v136, v11, 1, v0
	v_lshlrev_b32_e32 v0, 14, v12
	v_and_b32_e32 v0, 0xffff8000, v0
	s_waitcnt vmcnt(0)
	s_cmpk_lt_u32 s14, 0x100
	v_lshl_add_u32 v0, v13, 11, v0
	v_and_b32_e32 v1, 1, v12
	s_cselect_b64 s[24:25], -1, 0
	v_lshl_or_b32 v0, v1, 6, v0
	s_add_i32 s69, 0, 0x10000
	s_add_i32 s70, 0, 0x14000
	s_lshl_b32 s66, s26, 6
	s_ashr_i32 s67, s46, 31
	v_mov_b32_e32 v137, v131
	v_lshl_add_u32 v138, v14, 1, v0
	v_mov_b32_e32 v139, v131
	v_mov_b64_e32 v[140:141], 0x600
	v_mov_b64_e32 v[142:143], 0x5ff
	s_movk_i32 s68, 0xc1
	v_add_u32_e32 v179, s69, v178
	v_add_u32_e32 v180, s70, v178
	v_add_u32_e32 v181, 0, v2
	v_mov_b32_e32 v182, 0x358637bd
	v_mov_b32_e32 v183, 0x3e38aa3b
	s_mov_b32 s14, s15
	s_barrier
	s_branch .LBB0_949

.LBB0_951:
	s_ashr_i32 s27, s26, 31
	s_lshl_b64 s[30:31], s[26:27], 19
	s_add_u32 s30, s47, s30
	s_addc_u32 s31, s48, s31
	s_and_b64 s[36:37], s[4:5], exec
	s_cselect_b32 s27, s31, s7
	s_cselect_b32 s39, s30, s6
	s_ashr_i32 s29, s28, 31
	s_lshl_b64 s[36:37], s[28:29], 19
	s_add_u32 s36, s49, s36
	s_addc_u32 s37, s50, s37
	s_and_b64 s[44:45], s[4:5], exec
	s_cselect_b32 s29, s37, s41
	s_cselect_b32 s43, s36, s40
	s_add_u32 s6, s6, 0x40080
	s_addc_u32 s7, s7, 0
	s_add_u32 s71, s40, 0x100
	s_addc_u32 s72, s41, 0
	s_mov_b32 s73, -2
	ds_read_b128 v[144:147], v179
	ds_read_b128 v[148:151], v179 offset:1024
	ds_read_b128 v[152:155], v179 offset:2048
	ds_read_b128 v[156:159], v179 offset:3072
	ds_read_b128 v[160:163], v180
	ds_read_b128 v[164:167], v180 offset:1024
	ds_read_b128 v[168:171], v180 offset:2048
	ds_read_b128 v[172:175], v180 offset:3072
	s_add_u32 s40, s6, 0xfffc0080
	s_addc_u32 s41, s7, -1
	s_cmp_eq_u32 s73, 12
	s_cselect_b32 s45, s27, s41
	s_cselect_b32 s44, s39, s40
	s_cselect_b32 s41, s29, s72
	s_cselect_b32 s40, s43, s71
	v_lshl_add_u64 v[176:177], s[6:7], 0, v[136:137]
	s_add_i32 m0, s54, 0xc000
	ds_read_b128 v[184:187], v181
	ds_read_b128 v[188:191], v181 offset:1024
	ds_read_b128 v[192:195], v181 offset:2048
	ds_read_b128 v[196:199], v181 offset:3072
	ds_read_b128 v[200:203], v181 offset:4096
	ds_read_b128 v[204:207], v181 offset:5120
	ds_read_b128 v[208:211], v181 offset:6144
	ds_read_b128 v[212:215], v181 offset:7168
	global_load_lds_dwordx4 v[176:177], off
	s_add_i32 m0, s54, 0xe000
	v_lshl_add_u64 v[176:177], s[6:7], 0, v[138:139]
	global_load_lds_dwordx4 v[176:177], off
	s_waitcnt lgkmcnt(0)
	s_barrier
	s_setprio 1
	v_mfma_f32_16x16x32_bf16 v[124:127], v[144:147], v[184:187], 0
	v_mfma_f32_16x16x32_bf16 v[120:123], v[152:155], v[184:187], 0
	v_mfma_f32_16x16x32_bf16 v[108:111], v[144:147], v[192:195], 0
	v_mfma_f32_16x16x32_bf16 v[104:107], v[152:155], v[192:195], 0
	v_mfma_f32_16x16x32_bf16 v[92:95], v[144:147], v[200:203], 0
	v_mfma_f32_16x16x32_bf16 v[88:91], v[152:155], v[200:203], 0
	v_mfma_f32_16x16x32_bf16 v[76:79], v[144:147], v[208:211], 0
	v_mfma_f32_16x16x32_bf16 v[72:75], v[152:155], v[208:211], 0
	v_mfma_f32_16x16x32_bf16 v[124:127], v[148:151], v[188:191], v[124:127]
	v_mfma_f32_16x16x32_bf16 v[120:123], v[156:159], v[188:191], v[120:123]
	v_mfma_f32_16x16x32_bf16 v[108:111], v[148:151], v[196:199], v[108:111]
	v_mfma_f32_16x16x32_bf16 v[104:107], v[156:159], v[196:199], v[104:107]
	v_mfma_f32_16x16x32_bf16 v[92:95], v[148:151], v[204:207], v[92:95]
	v_mfma_f32_16x16x32_bf16 v[88:91], v[156:159], v[204:207], v[88:91]
	v_mfma_f32_16x16x32_bf16 v[76:79], v[148:151], v[212:215], v[76:79]
	v_mfma_f32_16x16x32_bf16 v[72:75], v[156:159], v[212:215], v[72:75]
	v_mfma_f32_16x16x32_bf16 v[116:119], v[160:163], v[184:187], 0
	v_mfma_f32_16x16x32_bf16 v[112:115], v[168:171], v[184:187], 0
	v_mfma_f32_16x16x32_bf16 v[100:103], v[160:163], v[192:195], 0
	v_mfma_f32_16x16x32_bf16 v[96:99], v[168:171], v[192:195], 0
	v_mfma_f32_16x16x32_bf16 v[84:87], v[160:163], v[200:203], 0
	v_mfma_f32_16x16x32_bf16 v[80:83], v[168:171], v[200:203], 0
	v_mfma_f32_16x16x32_bf16 v[68:71], v[160:163], v[208:211], 0
	v_mfma_f32_16x16x32_bf16 v[64:67], v[168:171], v[208:211], 0
	v_mfma_f32_16x16x32_bf16 v[116:119], v[164:167], v[188:191], v[116:119]
	v_mfma_f32_16x16x32_bf16 v[112:115], v[172:175], v[188:191], v[112:115]
	v_mfma_f32_16x16x32_bf16 v[100:103], v[164:167], v[196:199], v[100:103]
	v_mfma_f32_16x16x32_bf16 v[96:99], v[172:175], v[196:199], v[96:99]
	s_setprio 2
	s_barrier
	v_mfma_f32_16x16x32_bf16 v[84:87], v[164:167], v[204:207], v[84:87]
	v_mfma_f32_16x16x32_bf16 v[80:83], v[172:175], v[204:207], v[80:83]
	v_mfma_f32_16x16x32_bf16 v[68:71], v[164:167], v[212:215], v[68:71]
	v_mfma_f32_16x16x32_bf16 v[64:67], v[172:175], v[212:215], v[64:67]
	s_setprio 2
	s_add_i32 s74, s69, s51
	v_lshl_add_u64 v[176:177], s[40:41], 0, v[130:131]
	s_mov_b32 m0, s74
	ds_read_b128 v[184:187], v181 offset:16384
	ds_read_b128 v[188:191], v181 offset:17408
	ds_read_b128 v[192:195], v181 offset:18432
	ds_read_b128 v[196:199], v181 offset:19456
	ds_read_b128 v[200:203], v181 offset:20480
	ds_read_b128 v[204:207], v181 offset:21504
	ds_read_b128 v[208:211], v181 offset:22528
	ds_read_b128 v[212:215], v181 offset:23552
	global_load_lds_dwordx4 v[176:177], off
	s_add_i32 m0, s74, 0x2000
	s_add_u32 s74, s40, 0x40000
	v_lshl_add_u64 v[216:217], s[40:41], 0, v[134:135]
	s_addc_u32 s75, s41, 0
	s_add_i32 s76, s70, s51
	global_load_lds_dwordx4 v[216:217], off
	v_lshl_add_u64 v[218:219], s[74:75], 0, v[130:131]
	s_mov_b32 m0, s76
	v_lshl_add_u64 v[220:221], s[44:45], 0, v[132:133]
	global_load_lds_dwordx4 v[218:219], off
	s_add_i32 m0, s76, 0x2000
	v_lshl_add_u64 v[218:219], s[74:75], 0, v[134:135]
	global_load_lds_dwordx4 v[218:219], off
	s_mov_b32 m0, s54
	v_lshl_add_u64 v[218:219], s[44:45], 0, v[128:129]
	global_load_lds_dwordx4 v[218:219], off
	s_mov_b32 m0, s55
	s_nop 0
	global_load_lds_dwordx4 v[220:221], off
	s_waitcnt lgkmcnt(0)
	s_barrier
	s_setprio 1
	v_mfma_f32_16x16x32_bf16 v[60:63], v[144:147], v[184:187], 0
	v_mfma_f32_16x16x32_bf16 v[56:59], v[152:155], v[184:187], 0
	v_mfma_f32_16x16x32_bf16 v[44:47], v[144:147], v[192:195], 0
	v_mfma_f32_16x16x32_bf16 v[40:43], v[152:155], v[192:195], 0
	v_mfma_f32_16x16x32_bf16 v[28:31], v[144:147], v[200:203], 0
	v_mfma_f32_16x16x32_bf16 v[24:27], v[152:155], v[200:203], 0
	v_mfma_f32_16x16x32_bf16 v[12:15], v[144:147], v[208:211], 0
	v_mfma_f32_16x16x32_bf16 v[8:11], v[152:155], v[208:211], 0
	v_mfma_f32_16x16x32_bf16 v[60:63], v[148:151], v[188:191], v[60:63]
	v_mfma_f32_16x16x32_bf16 v[56:59], v[156:159], v[188:191], v[56:59]
	v_mfma_f32_16x16x32_bf16 v[44:47], v[148:151], v[196:199], v[44:47]
	v_mfma_f32_16x16x32_bf16 v[40:43], v[156:159], v[196:199], v[40:43]
	v_mfma_f32_16x16x32_bf16 v[28:31], v[148:151], v[204:207], v[28:31]
	v_mfma_f32_16x16x32_bf16 v[24:27], v[156:159], v[204:207], v[24:27]
	v_mfma_f32_16x16x32_bf16 v[12:15], v[148:151], v[212:215], v[12:15]
	v_mfma_f32_16x16x32_bf16 v[8:11], v[156:159], v[212:215], v[8:11]
	v_mfma_f32_16x16x32_bf16 v[52:55], v[160:163], v[184:187], 0
	v_mfma_f32_16x16x32_bf16 v[48:51], v[168:171], v[184:187], 0
	v_mfma_f32_16x16x32_bf16 v[36:39], v[160:163], v[192:195], 0
	v_mfma_f32_16x16x32_bf16 v[32:35], v[168:171], v[192:195], 0
	v_mfma_f32_16x16x32_bf16 v[20:23], v[160:163], v[200:203], 0
	v_mfma_f32_16x16x32_bf16 v[16:19], v[168:171], v[200:203], 0
	v_mfma_f32_16x16x32_bf16 v[4:7], v[160:163], v[208:211], 0
	v_mfma_f32_16x16x32_bf16 v[0:3], v[168:171], v[208:211], 0
	v_mfma_f32_16x16x32_bf16 v[52:55], v[164:167], v[188:191], v[52:55]
	v_mfma_f32_16x16x32_bf16 v[48:51], v[172:175], v[188:191], v[48:51]
	v_mfma_f32_16x16x32_bf16 v[36:39], v[164:167], v[196:199], v[36:39]
	v_mfma_f32_16x16x32_bf16 v[32:35], v[172:175], v[196:199], v[32:35]
	s_setprio 2
	s_barrier
	v_mfma_f32_16x16x32_bf16 v[20:23], v[164:167], v[204:207], v[20:23]
	v_mfma_f32_16x16x32_bf16 v[16:19], v[172:175], v[204:207], v[16:19]
	v_mfma_f32_16x16x32_bf16 v[4:7], v[164:167], v[212:215], v[4:7]
	v_mfma_f32_16x16x32_bf16 v[0:3], v[172:175], v[212:215], v[0:3]
	s_setprio 0
	s_add_i32 s74, 0, 0x18000
	s_add_i32 s75, 0, 0x1c000
	v_add_u32_e32 v156, s74, v178
	v_add_u32_e32 v172, s75, v178
	ds_read_b128 v[144:147], v156
	ds_read_b128 v[148:151], v156 offset:1024
	ds_read_b128 v[152:155], v156 offset:2048
	ds_read_b128 v[156:159], v156 offset:3072
	ds_read_b128 v[160:163], v172
	ds_read_b128 v[164:167], v172 offset:1024
	ds_read_b128 v[168:171], v172 offset:2048
	ds_read_b128 v[172:175], v172 offset:3072
	s_add_u32 s44, s44, 0x40000
	s_addc_u32 s45, s45, 0
	s_mov_b32 m0, s56
	v_lshl_add_u64 v[222:223], s[44:45], 0, v[128:129]
	ds_read_b128 v[184:187], v181 offset:32768
	ds_read_b128 v[188:191], v181 offset:33792
	ds_read_b128 v[192:195], v181 offset:34816
	ds_read_b128 v[196:199], v181 offset:35840
	ds_read_b128 v[200:203], v181 offset:36864
	ds_read_b128 v[204:207], v181 offset:37888
	ds_read_b128 v[208:211], v181 offset:38912
	ds_read_b128 v[212:215], v181 offset:39936
	global_load_lds_dwordx4 v[222:223], off
	s_mov_b32 m0, s57
	v_lshl_add_u64 v[222:223], s[44:45], 0, v[132:133]
	global_load_lds_dwordx4 v[222:223], off
	s_waitcnt vmcnt(8) lgkmcnt(0)
	s_barrier
	s_setprio 1
	v_mfma_f32_16x16x32_bf16 v[124:127], v[144:147], v[184:187], v[124:127]
	v_mfma_f32_16x16x32_bf16 v[120:123], v[152:155], v[184:187], v[120:123]
	v_mfma_f32_16x16x32_bf16 v[108:111], v[144:147], v[192:195], v[108:111]
	v_mfma_f32_16x16x32_bf16 v[104:107], v[152:155], v[192:195], v[104:107]
	v_mfma_f32_16x16x32_bf16 v[92:95], v[144:147], v[200:203], v[92:95]
	v_mfma_f32_16x16x32_bf16 v[88:91], v[152:155], v[200:203], v[88:91]
	v_mfma_f32_16x16x32_bf16 v[76:79], v[144:147], v[208:211], v[76:79]
	v_mfma_f32_16x16x32_bf16 v[72:75], v[152:155], v[208:211], v[72:75]
	v_mfma_f32_16x16x32_bf16 v[124:127], v[148:151], v[188:191], v[124:127]
	v_mfma_f32_16x16x32_bf16 v[120:123], v[156:159], v[188:191], v[120:123]
	v_mfma_f32_16x16x32_bf16 v[108:111], v[148:151], v[196:199], v[108:111]
	v_mfma_f32_16x16x32_bf16 v[104:107], v[156:159], v[196:199], v[104:107]
	v_mfma_f32_16x16x32_bf16 v[92:95], v[148:151], v[204:207], v[92:95]
	v_mfma_f32_16x16x32_bf16 v[88:91], v[156:159], v[204:207], v[88:91]
	v_mfma_f32_16x16x32_bf16 v[76:79], v[148:151], v[212:215], v[76:79]
	v_mfma_f32_16x16x32_bf16 v[72:75], v[156:159], v[212:215], v[72:75]
	v_mfma_f32_16x16x32_bf16 v[116:119], v[160:163], v[184:187], v[116:119]
	v_mfma_f32_16x16x32_bf16 v[112:115], v[168:171], v[184:187], v[112:115]
	v_mfma_f32_16x16x32_bf16 v[100:103], v[160:163], v[192:195], v[100:103]
	v_mfma_f32_16x16x32_bf16 v[96:99], v[168:171], v[192:195], v[96:99]
	v_mfma_f32_16x16x32_bf16 v[84:87], v[160:163], v[200:203], v[84:87]
	v_mfma_f32_16x16x32_bf16 v[80:83], v[168:171], v[200:203], v[80:83]
	v_mfma_f32_16x16x32_bf16 v[68:71], v[160:163], v[208:211], v[68:71]
	v_mfma_f32_16x16x32_bf16 v[64:67], v[168:171], v[208:211], v[64:67]
	v_mfma_f32_16x16x32_bf16 v[116:119], v[164:167], v[188:191], v[116:119]
	v_mfma_f32_16x16x32_bf16 v[112:115], v[172:175], v[188:191], v[112:115]
	v_mfma_f32_16x16x32_bf16 v[100:103], v[164:167], v[196:199], v[100:103]
	v_mfma_f32_16x16x32_bf16 v[96:99], v[172:175], v[196:199], v[96:99]
	s_setprio 2
	s_barrier
	v_mfma_f32_16x16x32_bf16 v[84:87], v[164:167], v[204:207], v[84:87]
	v_mfma_f32_16x16x32_bf16 v[80:83], v[172:175], v[204:207], v[80:83]
	v_mfma_f32_16x16x32_bf16 v[68:71], v[164:167], v[212:215], v[68:71]
	v_mfma_f32_16x16x32_bf16 v[64:67], v[172:175], v[212:215], v[64:67]
	s_setprio 2
	s_add_i32 s44, s74, s51
	v_lshl_add_u64 v[176:177], v[176:177], 0, s[22:23]
	s_mov_b32 m0, s44
	ds_read_b128 v[184:187], v181 offset:49152
	ds_read_b128 v[188:191], v181 offset:50176
	ds_read_b128 v[192:195], v181 offset:51200
	ds_read_b128 v[196:199], v181 offset:52224
	ds_read_b128 v[200:203], v181 offset:53248
	ds_read_b128 v[204:207], v181 offset:54272
	ds_read_b128 v[208:211], v181 offset:55296
	ds_read_b128 v[212:215], v181 offset:56320
	global_load_lds_dwordx4 v[176:177], off
	s_add_i32 m0, s44, 0x2000
	s_add_u32 s40, s40, 0x40080
	v_lshl_add_u64 v[176:177], v[216:217], 0, s[22:23]
	s_addc_u32 s41, s41, 0
	s_add_i32 s44, s75, s51
	global_load_lds_dwordx4 v[176:177], off
	s_mov_b32 m0, s44
	v_lshl_add_u64 v[176:177], s[40:41], 0, v[130:131]
	global_load_lds_dwordx4 v[176:177], off
	s_add_i32 m0, s44, 0x2000
	v_lshl_add_u64 v[176:177], s[40:41], 0, v[134:135]
	global_load_lds_dwordx4 v[176:177], off
	s_mov_b32 m0, s64
	v_lshl_add_u64 v[176:177], v[218:219], 0, s[22:23]
	global_load_lds_dwordx4 v[176:177], off
	s_mov_b32 m0, s65
	v_lshl_add_u64 v[176:177], v[220:221], 0, s[22:23]
	global_load_lds_dwordx4 v[176:177], off
	s_waitcnt vmcnt(8) lgkmcnt(0)
	s_barrier
	s_setprio 1
	v_mfma_f32_16x16x32_bf16 v[60:63], v[144:147], v[184:187], v[60:63]
	v_mfma_f32_16x16x32_bf16 v[56:59], v[152:155], v[184:187], v[56:59]
	v_mfma_f32_16x16x32_bf16 v[44:47], v[144:147], v[192:195], v[44:47]
	v_mfma_f32_16x16x32_bf16 v[40:43], v[152:155], v[192:195], v[40:43]
	v_mfma_f32_16x16x32_bf16 v[28:31], v[144:147], v[200:203], v[28:31]
	v_mfma_f32_16x16x32_bf16 v[24:27], v[152:155], v[200:203], v[24:27]
	v_mfma_f32_16x16x32_bf16 v[12:15], v[144:147], v[208:211], v[12:15]
	v_mfma_f32_16x16x32_bf16 v[8:11], v[152:155], v[208:211], v[8:11]
	v_mfma_f32_16x16x32_bf16 v[60:63], v[148:151], v[188:191], v[60:63]
	v_mfma_f32_16x16x32_bf16 v[56:59], v[156:159], v[188:191], v[56:59]
	v_mfma_f32_16x16x32_bf16 v[44:47], v[148:151], v[196:199], v[44:47]
	v_mfma_f32_16x16x32_bf16 v[40:43], v[156:159], v[196:199], v[40:43]
	v_mfma_f32_16x16x32_bf16 v[28:31], v[148:151], v[204:207], v[28:31]
	v_mfma_f32_16x16x32_bf16 v[24:27], v[156:159], v[204:207], v[24:27]
	v_mfma_f32_16x16x32_bf16 v[12:15], v[148:151], v[212:215], v[12:15]
	v_mfma_f32_16x16x32_bf16 v[8:11], v[156:159], v[212:215], v[8:11]
	v_mfma_f32_16x16x32_bf16 v[52:55], v[160:163], v[184:187], v[52:55]
	v_mfma_f32_16x16x32_bf16 v[48:51], v[168:171], v[184:187], v[48:51]
	v_mfma_f32_16x16x32_bf16 v[36:39], v[160:163], v[192:195], v[36:39]
	v_mfma_f32_16x16x32_bf16 v[32:35], v[168:171], v[192:195], v[32:35]
	v_mfma_f32_16x16x32_bf16 v[20:23], v[160:163], v[200:203], v[20:23]
	v_mfma_f32_16x16x32_bf16 v[16:19], v[168:171], v[200:203], v[16:19]
	v_mfma_f32_16x16x32_bf16 v[4:7], v[160:163], v[208:211], v[4:7]
	v_mfma_f32_16x16x32_bf16 v[0:3], v[168:171], v[208:211], v[0:3]
	v_mfma_f32_16x16x32_bf16 v[52:55], v[164:167], v[188:191], v[52:55]
	v_mfma_f32_16x16x32_bf16 v[48:51], v[172:175], v[188:191], v[48:51]
	v_mfma_f32_16x16x32_bf16 v[36:39], v[164:167], v[196:199], v[36:39]
	v_mfma_f32_16x16x32_bf16 v[32:35], v[172:175], v[196:199], v[32:35]
	s_setprio 2
	s_barrier
	v_mfma_f32_16x16x32_bf16 v[20:23], v[164:167], v[204:207], v[20:23]
	v_mfma_f32_16x16x32_bf16 v[16:19], v[172:175], v[204:207], v[16:19]
	v_mfma_f32_16x16x32_bf16 v[4:7], v[164:167], v[212:215], v[4:7]
	v_mfma_f32_16x16x32_bf16 v[0:3], v[172:175], v[212:215], v[0:3]
	s_setprio 0
	s_add_i32 s73, s73, 2
	s_add_u32 s6, s6, 0x100
	s_addc_u32 s7, s7, 0
	s_add_u32 s71, s71, 0x100
	s_addc_u32 s72, s72, 0
	s_cmp_gt_u32 s73, 13

.LBB0_1136:
	s_add_u32 s12, s4, 0x14800000
	s_addc_u32 s13, s5, 0
	s_add_u32 s14, s4, 0x140000
	s_addc_u32 s15, s5, 0
	s_lshl_b32 s4, s6, 5
	s_mov_b64 s[18:19], 0x80
	s_lshl_b32 s56, s16, 6
	s_lshl_b32 s20, s16, 13
	s_and_b32 s16, s4, 0x60
	s_add_i32 m0, s50, 0x18000
	v_lshl_add_u64 v[6:7], v[6:7], 0, s[18:19]
	s_lshl_b32 s6, s16, 7
	s_waitcnt vmcnt(2)
	s_barrier
	global_load_lds_dwordx4 v[6:7], off
	v_lshl_add_u64 v[4:5], v[4:5], 0, s[18:19]
	s_add_i32 m0, s50, 0x1a000
	s_add_i32 s57, s50, 0x8000
	s_add_i32 s58, s50, 0xa000
	global_load_lds_dwordx4 v[4:5], off
	v_lshl_add_u64 v[0:1], v[0:1], 0, s[18:19]
	s_mov_b32 m0, s57
	s_add_u32 s4, s40, 0x40080
	global_load_lds_dwordx4 v[0:1], off
	v_lshl_add_u64 v[0:1], v[2:3], 0, s[18:19]
	s_mov_b32 m0, s58
	s_addc_u32 s5, s41, 0
	global_load_lds_dwordx4 v[0:1], off
	s_add_i32 m0, s50, 0x1c000
	v_lshl_add_u64 v[0:1], s[4:5], 0, v[186:187]
	global_load_lds_dwordx4 v[0:1], off
	v_lshl_add_u64 v[0:1], s[4:5], 0, v[190:191]
	s_add_i32 m0, s50, 0x1e000
	s_movk_i32 s4, 0x3c0
	global_load_lds_dwordx4 v[0:1], off
	v_and_b32_e32 v0, 48, v8
	v_lshlrev_b32_e32 v1, 6, v8
	v_and_or_b32 v0, v1, s4, v0
	v_lshlrev_b32_e32 v1, 2, v8
	v_and_b32_e32 v1, 32, v1
	v_bitop3_b32 v2, v0, s20, v1 bitop3:0xde
	v_bitop3_b32 v232, s6, v0, v1 bitop3:0xf6
	v_lshlrev_b32_e32 v0, 14, v9
	v_and_b32_e32 v0, 0xffff8000, v0
	v_lshl_add_u32 v0, v10, 11, v0
	v_and_b32_e32 v1, 1, v9
	v_lshl_or_b32 v0, v1, 6, v0
	s_cmpk_lt_u32 s17, 0x100
	v_lshl_add_u32 v192, v11, 1, v0
	v_lshlrev_b32_e32 v0, 14, v12
	s_cselect_b64 s[20:21], -1, 0
	s_ashr_i32 s59, s44, 31
	s_lshl_b32 s4, s16, 1
	v_and_b32_e32 v0, 0xffff8000, v0
	s_waitcnt vmcnt(0)
	s_add_u32 s60, s12, s4
	v_lshl_add_u32 v0, v13, 11, v0
	v_and_b32_e32 v1, 1, v12
	s_addc_u32 s61, s13, 0
	v_lshl_or_b32 v0, v1, 6, v0
	s_add_i32 s62, 0, 0x10000
	s_add_i32 s63, 0, 0x14000
	s_mov_b32 s17, s7
	v_mov_b32_e32 v193, v187
	v_lshl_add_u32 v194, v14, 1, v0
	v_mov_b32_e32 v195, v187
	v_mov_b64_e32 v[196:197], 0x200
	v_mov_b64_e32 v[198:199], 0x1ff
	v_add_u32_e32 v233, s62, v232
	v_add_u32_e32 v234, s63, v232
	v_add_u32_e32 v235, 0, v2
	s_mov_b32 s6, s7
	s_barrier
	s_branch .LBB0_1139

.LBB0_1145:
	s_ashr_i32 s23, s22, 31
	s_lshl_b64 s[26:27], s[22:23], 19
	s_add_u32 s26, s45, s26
	s_addc_u32 s27, s46, s27
	s_and_b64 s[28:29], s[4:5], exec
	s_cselect_b32 s23, s27, s39
	s_cselect_b32 s31, s26, s38
	s_ashr_i32 s25, s24, 31
	s_lshl_b64 s[28:29], s[24:25], 19
	s_add_u32 s28, s47, s28
	s_addc_u32 s29, s48, s29
	s_and_b64 s[42:43], s[4:5], exec
	s_cselect_b32 s25, s29, s41
	s_cselect_b32 s37, s28, s40
	s_add_u32 s38, s38, 0x40080
	s_addc_u32 s39, s39, 0
	s_add_u32 s64, s40, 0x100
	s_addc_u32 s65, s41, 0
	s_mov_b32 s66, -2
	ds_read_b128 v[120:123], v233
	ds_read_b128 v[132:135], v233 offset:1024
	ds_read_b128 v[136:139], v233 offset:2048
	ds_read_b128 v[140:143], v233 offset:3072
	ds_read_b128 v[144:147], v234
	ds_read_b128 v[148:151], v234 offset:1024
	ds_read_b128 v[152:155], v234 offset:2048
	ds_read_b128 v[156:159], v234 offset:3072
	s_add_u32 s40, s38, 0xfffc0080
	s_addc_u32 s41, s39, -1
	s_cmp_eq_u32 s66, 12
	s_cselect_b32 s43, s23, s41
	s_cselect_b32 s42, s31, s40
	s_cselect_b32 s41, s25, s65
	s_cselect_b32 s40, s37, s64
	v_lshl_add_u64 v[208:209], s[38:39], 0, v[192:193]
	s_add_i32 m0, s50, 0xc000
	ds_read_b128 v[160:163], v235
	ds_read_b128 v[164:167], v235 offset:1024
	ds_read_b128 v[168:171], v235 offset:2048
	ds_read_b128 v[172:175], v235 offset:3072
	ds_read_b128 v[176:179], v235 offset:4096
	ds_read_b128 v[180:183], v235 offset:5120
	ds_read_b128 v[200:203], v235 offset:6144
	ds_read_b128 v[204:207], v235 offset:7168
	global_load_lds_dwordx4 v[208:209], off
	s_add_i32 m0, s50, 0xe000
	v_lshl_add_u64 v[208:209], s[38:39], 0, v[194:195]
	global_load_lds_dwordx4 v[208:209], off
	s_waitcnt lgkmcnt(0)
	s_barrier
	s_setprio 1
	v_mfma_f32_16x16x32_bf16 v[128:131], v[120:123], v[160:163], 0
	v_mfma_f32_16x16x32_bf16 v[124:127], v[136:139], v[160:163], 0
	v_mfma_f32_16x16x32_bf16 v[108:111], v[120:123], v[168:171], 0
	v_mfma_f32_16x16x32_bf16 v[104:107], v[136:139], v[168:171], 0
	v_mfma_f32_16x16x32_bf16 v[92:95], v[120:123], v[176:179], 0
	v_mfma_f32_16x16x32_bf16 v[88:91], v[136:139], v[176:179], 0
	v_mfma_f32_16x16x32_bf16 v[76:79], v[120:123], v[200:203], 0
	v_mfma_f32_16x16x32_bf16 v[72:75], v[136:139], v[200:203], 0
	v_mfma_f32_16x16x32_bf16 v[128:131], v[132:135], v[164:167], v[128:131]
	v_mfma_f32_16x16x32_bf16 v[124:127], v[140:143], v[164:167], v[124:127]
	v_mfma_f32_16x16x32_bf16 v[108:111], v[132:135], v[172:175], v[108:111]
	v_mfma_f32_16x16x32_bf16 v[104:107], v[140:143], v[172:175], v[104:107]
	v_mfma_f32_16x16x32_bf16 v[92:95], v[132:135], v[180:183], v[92:95]
	v_mfma_f32_16x16x32_bf16 v[88:91], v[140:143], v[180:183], v[88:91]
	v_mfma_f32_16x16x32_bf16 v[76:79], v[132:135], v[204:207], v[76:79]
	v_mfma_f32_16x16x32_bf16 v[72:75], v[140:143], v[204:207], v[72:75]
	v_mfma_f32_16x16x32_bf16 v[116:119], v[144:147], v[160:163], 0
	v_mfma_f32_16x16x32_bf16 v[112:115], v[152:155], v[160:163], 0
	v_mfma_f32_16x16x32_bf16 v[100:103], v[144:147], v[168:171], 0
	v_mfma_f32_16x16x32_bf16 v[96:99], v[152:155], v[168:171], 0
	v_mfma_f32_16x16x32_bf16 v[84:87], v[144:147], v[176:179], 0
	v_mfma_f32_16x16x32_bf16 v[80:83], v[152:155], v[176:179], 0
	v_mfma_f32_16x16x32_bf16 v[68:71], v[144:147], v[200:203], 0
	v_mfma_f32_16x16x32_bf16 v[64:67], v[152:155], v[200:203], 0
	v_mfma_f32_16x16x32_bf16 v[116:119], v[148:151], v[164:167], v[116:119]
	v_mfma_f32_16x16x32_bf16 v[112:115], v[156:159], v[164:167], v[112:115]
	v_mfma_f32_16x16x32_bf16 v[100:103], v[148:151], v[172:175], v[100:103]
	v_mfma_f32_16x16x32_bf16 v[96:99], v[156:159], v[172:175], v[96:99]
	s_setprio 2
	s_barrier
	v_mfma_f32_16x16x32_bf16 v[84:87], v[148:151], v[180:183], v[84:87]
	v_mfma_f32_16x16x32_bf16 v[80:83], v[156:159], v[180:183], v[80:83]
	v_mfma_f32_16x16x32_bf16 v[68:71], v[148:151], v[204:207], v[68:71]
	v_mfma_f32_16x16x32_bf16 v[64:67], v[156:159], v[204:207], v[64:67]
	s_setprio 2
	s_add_i32 s67, s62, s49
	v_lshl_add_u64 v[208:209], s[40:41], 0, v[186:187]
	s_mov_b32 m0, s67
	ds_read_b128 v[160:163], v235 offset:16384
	ds_read_b128 v[164:167], v235 offset:17408
	ds_read_b128 v[168:171], v235 offset:18432
	ds_read_b128 v[172:175], v235 offset:19456
	ds_read_b128 v[176:179], v235 offset:20480
	ds_read_b128 v[180:183], v235 offset:21504
	ds_read_b128 v[200:203], v235 offset:22528
	ds_read_b128 v[204:207], v235 offset:23552
	global_load_lds_dwordx4 v[208:209], off
	s_add_i32 m0, s67, 0x2000
	s_add_u32 s68, s40, 0x40000
	v_lshl_add_u64 v[210:211], s[40:41], 0, v[190:191]
	s_addc_u32 s69, s41, 0
	s_add_i32 s67, s63, s49
	global_load_lds_dwordx4 v[210:211], off
	v_lshl_add_u64 v[212:213], s[68:69], 0, v[186:187]
	s_mov_b32 m0, s67
	v_lshl_add_u64 v[214:215], s[42:43], 0, v[188:189]
	global_load_lds_dwordx4 v[212:213], off
	s_add_i32 m0, s67, 0x2000
	v_lshl_add_u64 v[212:213], s[68:69], 0, v[190:191]
	global_load_lds_dwordx4 v[212:213], off
	s_mov_b32 m0, s50
	v_lshl_add_u64 v[212:213], s[42:43], 0, v[184:185]
	global_load_lds_dwordx4 v[212:213], off
	s_mov_b32 m0, s51
	s_nop 0
	global_load_lds_dwordx4 v[214:215], off
	s_waitcnt lgkmcnt(0)
	s_barrier
	s_setprio 1
	v_mfma_f32_16x16x32_bf16 v[60:63], v[120:123], v[160:163], 0
	v_mfma_f32_16x16x32_bf16 v[56:59], v[136:139], v[160:163], 0
	v_mfma_f32_16x16x32_bf16 v[44:47], v[120:123], v[168:171], 0
	v_mfma_f32_16x16x32_bf16 v[40:43], v[136:139], v[168:171], 0
	v_mfma_f32_16x16x32_bf16 v[28:31], v[120:123], v[176:179], 0
	v_mfma_f32_16x16x32_bf16 v[24:27], v[136:139], v[176:179], 0
	v_mfma_f32_16x16x32_bf16 v[12:15], v[120:123], v[200:203], 0
	v_mfma_f32_16x16x32_bf16 v[8:11], v[136:139], v[200:203], 0
	v_mfma_f32_16x16x32_bf16 v[60:63], v[132:135], v[164:167], v[60:63]
	v_mfma_f32_16x16x32_bf16 v[56:59], v[140:143], v[164:167], v[56:59]
	v_mfma_f32_16x16x32_bf16 v[44:47], v[132:135], v[172:175], v[44:47]
	v_mfma_f32_16x16x32_bf16 v[40:43], v[140:143], v[172:175], v[40:43]
	v_mfma_f32_16x16x32_bf16 v[28:31], v[132:135], v[180:183], v[28:31]
	v_mfma_f32_16x16x32_bf16 v[24:27], v[140:143], v[180:183], v[24:27]
	v_mfma_f32_16x16x32_bf16 v[12:15], v[132:135], v[204:207], v[12:15]
	v_mfma_f32_16x16x32_bf16 v[8:11], v[140:143], v[204:207], v[8:11]
	v_mfma_f32_16x16x32_bf16 v[52:55], v[144:147], v[160:163], 0
	v_mfma_f32_16x16x32_bf16 v[48:51], v[152:155], v[160:163], 0
	v_mfma_f32_16x16x32_bf16 v[36:39], v[144:147], v[168:171], 0
	v_mfma_f32_16x16x32_bf16 v[32:35], v[152:155], v[168:171], 0
	v_mfma_f32_16x16x32_bf16 v[20:23], v[144:147], v[176:179], 0
	v_mfma_f32_16x16x32_bf16 v[16:19], v[152:155], v[176:179], 0
	v_mfma_f32_16x16x32_bf16 v[4:7], v[144:147], v[200:203], 0
	v_mfma_f32_16x16x32_bf16 v[0:3], v[152:155], v[200:203], 0
	v_mfma_f32_16x16x32_bf16 v[52:55], v[148:151], v[164:167], v[52:55]
	v_mfma_f32_16x16x32_bf16 v[48:51], v[156:159], v[164:167], v[48:51]
	v_mfma_f32_16x16x32_bf16 v[36:39], v[148:151], v[172:175], v[36:39]
	v_mfma_f32_16x16x32_bf16 v[32:35], v[156:159], v[172:175], v[32:35]
	s_setprio 2
	s_barrier
	v_mfma_f32_16x16x32_bf16 v[20:23], v[148:151], v[180:183], v[20:23]
	v_mfma_f32_16x16x32_bf16 v[16:19], v[156:159], v[180:183], v[16:19]
	v_mfma_f32_16x16x32_bf16 v[4:7], v[148:151], v[204:207], v[4:7]
	v_mfma_f32_16x16x32_bf16 v[0:3], v[156:159], v[204:207], v[0:3]
	s_setprio 0
	s_add_i32 s67, 0, 0x18000
	s_add_i32 s68, 0, 0x1c000
	v_add_u32_e32 v140, s67, v232
	v_add_u32_e32 v156, s68, v232
	ds_read_b128 v[120:123], v140
	ds_read_b128 v[132:135], v140 offset:1024
	ds_read_b128 v[136:139], v140 offset:2048
	ds_read_b128 v[140:143], v140 offset:3072
	ds_read_b128 v[144:147], v156
	ds_read_b128 v[148:151], v156 offset:1024
	ds_read_b128 v[152:155], v156 offset:2048
	ds_read_b128 v[156:159], v156 offset:3072
	s_add_u32 s42, s42, 0x40000
	s_addc_u32 s43, s43, 0
	s_mov_b32 m0, s54
	v_lshl_add_u64 v[216:217], s[42:43], 0, v[184:185]
	ds_read_b128 v[160:163], v235 offset:32768
	ds_read_b128 v[164:167], v235 offset:33792
	ds_read_b128 v[168:171], v235 offset:34816
	ds_read_b128 v[172:175], v235 offset:35840
	ds_read_b128 v[176:179], v235 offset:36864
	ds_read_b128 v[180:183], v235 offset:37888
	ds_read_b128 v[200:203], v235 offset:38912
	ds_read_b128 v[204:207], v235 offset:39936
	global_load_lds_dwordx4 v[216:217], off
	s_mov_b32 m0, s55
	v_lshl_add_u64 v[216:217], s[42:43], 0, v[188:189]
	global_load_lds_dwordx4 v[216:217], off
	s_waitcnt vmcnt(8) lgkmcnt(0)
	s_barrier
	s_setprio 1
	v_mfma_f32_16x16x32_bf16 v[128:131], v[120:123], v[160:163], v[128:131]
	v_mfma_f32_16x16x32_bf16 v[124:127], v[136:139], v[160:163], v[124:127]
	v_mfma_f32_16x16x32_bf16 v[108:111], v[120:123], v[168:171], v[108:111]
	v_mfma_f32_16x16x32_bf16 v[104:107], v[136:139], v[168:171], v[104:107]
	v_mfma_f32_16x16x32_bf16 v[92:95], v[120:123], v[176:179], v[92:95]
	v_mfma_f32_16x16x32_bf16 v[88:91], v[136:139], v[176:179], v[88:91]
	v_mfma_f32_16x16x32_bf16 v[76:79], v[120:123], v[200:203], v[76:79]
	v_mfma_f32_16x16x32_bf16 v[72:75], v[136:139], v[200:203], v[72:75]
	v_mfma_f32_16x16x32_bf16 v[128:131], v[132:135], v[164:167], v[128:131]
	v_mfma_f32_16x16x32_bf16 v[124:127], v[140:143], v[164:167], v[124:127]
	v_mfma_f32_16x16x32_bf16 v[108:111], v[132:135], v[172:175], v[108:111]
	v_mfma_f32_16x16x32_bf16 v[104:107], v[140:143], v[172:175], v[104:107]
	v_mfma_f32_16x16x32_bf16 v[92:95], v[132:135], v[180:183], v[92:95]
	v_mfma_f32_16x16x32_bf16 v[88:91], v[140:143], v[180:183], v[88:91]
	v_mfma_f32_16x16x32_bf16 v[76:79], v[132:135], v[204:207], v[76:79]
	v_mfma_f32_16x16x32_bf16 v[72:75], v[140:143], v[204:207], v[72:75]
	v_mfma_f32_16x16x32_bf16 v[116:119], v[144:147], v[160:163], v[116:119]
	v_mfma_f32_16x16x32_bf16 v[112:115], v[152:155], v[160:163], v[112:115]
	v_mfma_f32_16x16x32_bf16 v[100:103], v[144:147], v[168:171], v[100:103]
	v_mfma_f32_16x16x32_bf16 v[96:99], v[152:155], v[168:171], v[96:99]
	v_mfma_f32_16x16x32_bf16 v[84:87], v[144:147], v[176:179], v[84:87]
	v_mfma_f32_16x16x32_bf16 v[80:83], v[152:155], v[176:179], v[80:83]
	v_mfma_f32_16x16x32_bf16 v[68:71], v[144:147], v[200:203], v[68:71]
	v_mfma_f32_16x16x32_bf16 v[64:67], v[152:155], v[200:203], v[64:67]
	v_mfma_f32_16x16x32_bf16 v[116:119], v[148:151], v[164:167], v[116:119]
	v_mfma_f32_16x16x32_bf16 v[112:115], v[156:159], v[164:167], v[112:115]
	v_mfma_f32_16x16x32_bf16 v[100:103], v[148:151], v[172:175], v[100:103]
	v_mfma_f32_16x16x32_bf16 v[96:99], v[156:159], v[172:175], v[96:99]
	s_setprio 2
	s_barrier
	v_mfma_f32_16x16x32_bf16 v[84:87], v[148:151], v[180:183], v[84:87]
	v_mfma_f32_16x16x32_bf16 v[80:83], v[156:159], v[180:183], v[80:83]
	v_mfma_f32_16x16x32_bf16 v[68:71], v[148:151], v[204:207], v[68:71]
	v_mfma_f32_16x16x32_bf16 v[64:67], v[156:159], v[204:207], v[64:67]
	s_setprio 2
	s_add_i32 s42, s67, s49
	v_lshl_add_u64 v[208:209], v[208:209], 0, s[18:19]
	s_mov_b32 m0, s42
	ds_read_b128 v[160:163], v235 offset:49152
	ds_read_b128 v[164:167], v235 offset:50176
	ds_read_b128 v[168:171], v235 offset:51200
	ds_read_b128 v[172:175], v235 offset:52224
	ds_read_b128 v[176:179], v235 offset:53248
	ds_read_b128 v[180:183], v235 offset:54272
	ds_read_b128 v[200:203], v235 offset:55296
	ds_read_b128 v[204:207], v235 offset:56320
	global_load_lds_dwordx4 v[208:209], off
	s_add_i32 m0, s42, 0x2000
	s_add_u32 s40, s40, 0x40080
	v_lshl_add_u64 v[208:209], v[210:211], 0, s[18:19]
	s_addc_u32 s41, s41, 0
	s_add_i32 s42, s68, s49
	global_load_lds_dwordx4 v[208:209], off
	s_mov_b32 m0, s42
	v_lshl_add_u64 v[208:209], s[40:41], 0, v[186:187]
	global_load_lds_dwordx4 v[208:209], off
	s_add_i32 m0, s42, 0x2000
	v_lshl_add_u64 v[208:209], s[40:41], 0, v[190:191]
	global_load_lds_dwordx4 v[208:209], off
	s_mov_b32 m0, s57
	v_lshl_add_u64 v[208:209], v[212:213], 0, s[18:19]
	global_load_lds_dwordx4 v[208:209], off
	s_mov_b32 m0, s58
	v_lshl_add_u64 v[208:209], v[214:215], 0, s[18:19]
	global_load_lds_dwordx4 v[208:209], off
	s_waitcnt vmcnt(8) lgkmcnt(0)
	s_barrier
	s_setprio 1
	v_mfma_f32_16x16x32_bf16 v[60:63], v[120:123], v[160:163], v[60:63]
	v_mfma_f32_16x16x32_bf16 v[56:59], v[136:139], v[160:163], v[56:59]
	v_mfma_f32_16x16x32_bf16 v[44:47], v[120:123], v[168:171], v[44:47]
	v_mfma_f32_16x16x32_bf16 v[40:43], v[136:139], v[168:171], v[40:43]
	v_mfma_f32_16x16x32_bf16 v[28:31], v[120:123], v[176:179], v[28:31]
	v_mfma_f32_16x16x32_bf16 v[24:27], v[136:139], v[176:179], v[24:27]
	v_mfma_f32_16x16x32_bf16 v[12:15], v[120:123], v[200:203], v[12:15]
	v_mfma_f32_16x16x32_bf16 v[8:11], v[136:139], v[200:203], v[8:11]
	v_mfma_f32_16x16x32_bf16 v[60:63], v[132:135], v[164:167], v[60:63]
	v_mfma_f32_16x16x32_bf16 v[56:59], v[140:143], v[164:167], v[56:59]
	v_mfma_f32_16x16x32_bf16 v[44:47], v[132:135], v[172:175], v[44:47]
	v_mfma_f32_16x16x32_bf16 v[40:43], v[140:143], v[172:175], v[40:43]
	v_mfma_f32_16x16x32_bf16 v[28:31], v[132:135], v[180:183], v[28:31]
	v_mfma_f32_16x16x32_bf16 v[24:27], v[140:143], v[180:183], v[24:27]
	v_mfma_f32_16x16x32_bf16 v[12:15], v[132:135], v[204:207], v[12:15]
	v_mfma_f32_16x16x32_bf16 v[8:11], v[140:143], v[204:207], v[8:11]
	v_mfma_f32_16x16x32_bf16 v[52:55], v[144:147], v[160:163], v[52:55]
	v_mfma_f32_16x16x32_bf16 v[48:51], v[152:155], v[160:163], v[48:51]
	v_mfma_f32_16x16x32_bf16 v[36:39], v[144:147], v[168:171], v[36:39]
	v_mfma_f32_16x16x32_bf16 v[32:35], v[152:155], v[168:171], v[32:35]
	v_mfma_f32_16x16x32_bf16 v[20:23], v[144:147], v[176:179], v[20:23]
	v_mfma_f32_16x16x32_bf16 v[16:19], v[152:155], v[176:179], v[16:19]
	v_mfma_f32_16x16x32_bf16 v[4:7], v[144:147], v[200:203], v[4:7]
	v_mfma_f32_16x16x32_bf16 v[0:3], v[152:155], v[200:203], v[0:3]
	v_mfma_f32_16x16x32_bf16 v[52:55], v[148:151], v[164:167], v[52:55]
	v_mfma_f32_16x16x32_bf16 v[48:51], v[156:159], v[164:167], v[48:51]
	v_mfma_f32_16x16x32_bf16 v[36:39], v[148:151], v[172:175], v[36:39]
	v_mfma_f32_16x16x32_bf16 v[32:35], v[156:159], v[172:175], v[32:35]
	s_setprio 2
	s_barrier
	v_mfma_f32_16x16x32_bf16 v[20:23], v[148:151], v[180:183], v[20:23]
	v_mfma_f32_16x16x32_bf16 v[16:19], v[156:159], v[180:183], v[16:19]
	v_mfma_f32_16x16x32_bf16 v[4:7], v[148:151], v[204:207], v[4:7]
	v_mfma_f32_16x16x32_bf16 v[0:3], v[156:159], v[204:207], v[0:3]
	s_setprio 0
	s_add_i32 s66, s66, 2
	s_add_u32 s38, s38, 0x100
	s_addc_u32 s39, s39, 0
	s_add_u32 s64, s64, 0x100
	s_addc_u32 s65, s65, 0
	s_cmp_gt_u32 s66, 13

.LBB0_1224:
	s_add_u32 s12, s4, 0x140000
	s_addc_u32 s13, s5, 0
	s_add_u32 s14, s4, 0x4800000
	s_addc_u32 s15, s5, 0
	s_lshl_b32 s56, s17, 6
	s_lshl_b32 s19, s17, 13
	s_lshl_b32 s4, s16, 5
	s_mov_b64 s[16:17], 0x80
	s_and_b32 s20, s4, 0x60
	s_add_i32 m0, s50, 0x18000
	v_lshl_add_u64 v[6:7], v[6:7], 0, s[16:17]
	s_lshl_b32 s22, s20, 7
	s_waitcnt vmcnt(2)
	s_barrier
	global_load_lds_dwordx4 v[6:7], off
	v_lshl_add_u64 v[4:5], v[4:5], 0, s[16:17]
	s_add_i32 m0, s50, 0x1a000
	s_add_i32 s57, s50, 0x8000
	s_add_i32 s58, s50, 0xa000
	global_load_lds_dwordx4 v[4:5], off
	v_lshl_add_u64 v[0:1], v[0:1], 0, s[16:17]
	s_mov_b32 m0, s57
	s_add_u32 s4, s38, 0x40080
	global_load_lds_dwordx4 v[0:1], off
	v_lshl_add_u64 v[0:1], v[2:3], 0, s[16:17]
	s_mov_b32 m0, s58
	s_addc_u32 s5, s39, 0
	global_load_lds_dwordx4 v[0:1], off
	s_add_i32 m0, s50, 0x1c000
	v_lshl_add_u64 v[0:1], s[4:5], 0, v[132:133]
	global_load_lds_dwordx4 v[0:1], off
	v_lshl_add_u64 v[0:1], s[4:5], 0, v[128:129]
	s_add_i32 m0, s50, 0x1e000
	s_movk_i32 s4, 0x3c0
	global_load_lds_dwordx4 v[0:1], off
	v_and_b32_e32 v0, 48, v8
	v_lshlrev_b32_e32 v1, 6, v8
	v_and_or_b32 v0, v1, s4, v0
	v_lshlrev_b32_e32 v1, 2, v8
	v_and_b32_e32 v1, 32, v1
	v_bitop3_b32 v2, v0, s19, v1 bitop3:0xde
	v_bitop3_b32 v162, s22, v0, v1 bitop3:0xf6
	v_lshlrev_b32_e32 v0, 14, v13
	v_and_b32_e32 v0, 0xffff8000, v0
	v_lshl_add_u32 v0, v12, 11, v0
	v_and_b32_e32 v1, 1, v13
	v_lshl_or_b32 v0, v1, 6, v0
	v_lshl_add_u32 v136, v14, 1, v0
	v_lshlrev_b32_e32 v0, 14, v9
	v_and_b32_e32 v0, 0xffff8000, v0
	s_waitcnt vmcnt(0)
	s_cmpk_lt_u32 s18, 0x100
	v_lshl_add_u32 v0, v10, 11, v0
	v_and_b32_e32 v1, 1, v9
	s_cselect_b64 s[18:19], -1, 0
	v_lshl_or_b32 v0, v1, 6, v0
	s_add_i32 s59, 0, 0x10000
	s_add_i32 s60, 0, 0x14000
	s_sext_i32_i16 s21, s6
	v_mov_b32_e32 v137, v133
	v_lshl_add_u32 v138, v11, 1, v0
	v_mov_b32_e32 v139, v133
	v_mov_b64_e32 v[140:141], 0xb00
	v_mov_b64_e32 v[142:143], 0xaff
	v_add_u32_e32 v163, s59, v162
	v_add_u32_e32 v164, s60, v162
	v_add_u32_e32 v165, 0, v2
	v_mov_b32_e32 v166, 0x358637bd
	s_movk_i32 s61, 0x1600
	s_lshl_b32 s20, s20, 1
	s_mov_b32 s6, s7
	s_barrier
	s_branch .LBB0_1227

.LBB0_1296:
	s_lshl_b32 s1, s1, 5
	s_mov_b64 s[16:17], 0x80
	s_and_b32 s14, s1, 0x60
	s_add_i32 m0, s36, 0x18000
	v_lshl_add_u64 v[6:7], v[6:7], 0, s[16:17]
	s_lshl_b32 s40, s5, 6
	s_lshl_b32 s5, s5, 13
	s_lshl_b32 s1, s14, 7
	s_waitcnt vmcnt(2)
	s_barrier
	global_load_lds_dwordx4 v[6:7], off
	v_lshl_add_u64 v[4:5], v[4:5], 0, s[16:17]
	s_add_i32 m0, s36, 0x1a000
	s_add_i32 s41, s36, 0x8000
	s_add_i32 s42, s36, 0xa000
	global_load_lds_dwordx4 v[4:5], off
	v_lshl_add_u64 v[0:1], v[0:1], 0, s[16:17]
	s_mov_b32 m0, s41
	s_add_u32 s18, s26, 0xb0080
	global_load_lds_dwordx4 v[0:1], off
	v_lshl_add_u64 v[0:1], v[2:3], 0, s[16:17]
	s_mov_b32 m0, s42
	s_addc_u32 s19, s27, 0
	global_load_lds_dwordx4 v[0:1], off
	s_add_i32 m0, s36, 0x1c000
	v_lshl_add_u64 v[0:1], s[18:19], 0, v[166:167]
	global_load_lds_dwordx4 v[0:1], off
	v_lshl_add_u64 v[0:1], s[18:19], 0, v[170:171]
	s_add_i32 m0, s36, 0x1e000
	s_sext_i32_i8 s50, s4
	global_load_lds_dwordx4 v[0:1], off
	v_and_b32_e32 v0, 48, v8
	v_lshlrev_b32_e32 v1, 6, v8
	s_movk_i32 s4, 0x3c0
	v_and_or_b32 v0, v1, s4, v0
	v_lshlrev_b32_e32 v1, 2, v8
	v_and_b32_e32 v1, 32, v1
	s_cmpk_lt_u32 s6, 0x100
	v_bitop3_b32 v196, s1, v0, v1 bitop3:0xf6
	s_cselect_b64 s[18:19], -1, 0
	s_lshl_b32 s1, s14, 1
	s_add_u32 s1, s10, s1
	s_addc_u32 s6, s11, 0
	v_bitop3_b32 v2, v0, s5, v1 bitop3:0xde
	s_add_u32 s43, s1, 0x14800000
	v_lshrrev_b32_e32 v1, 1, v9
	v_mul_lo_u32 v0, v11, s0
	s_mov_b32 s1, 0xb000
	v_mad_u64_u32 v[0:1], s[20:21], v1, s1, v[0:1]
	v_or_b32_e32 v0, v0, v10
	s_mov_b64 s[4:5], 0xb0080
	v_add_lshl_u32 v0, v0, v12, 1
	v_mov_b32_e32 v1, v167
	v_lshl_add_u64 v[172:173], v[0:1], 0, s[4:5]
	v_lshrrev_b32_e32 v1, 1, v13
	v_mul_lo_u32 v0, v14, s0
	s_addc_u32 s44, s6, 0
	v_mad_u64_u32 v[0:1], s[0:1], v1, s1, v[0:1]
	s_waitcnt vmcnt(0)
	s_cmp_lg_u64 s[8:9], 0
	v_or_b32_e32 v0, v0, v15
	s_cselect_b64 s[10:11], -1, 0
	v_add_lshl_u32 v0, v0, v16, 1
	v_mov_b32_e32 v1, v167
	s_add_i32 s45, 0, 0x10000
	s_add_i32 s46, 0, 0x14000
	s_mov_b32 s15, s7
	v_lshl_add_u64 v[174:175], v[0:1], 0, s[4:5]
	v_mov_b64_e32 v[176:177], 0x200
	v_mov_b64_e32 v[178:179], 0x1ff
	v_add_u32_e32 v197, s45, v196
	v_add_u32_e32 v198, s46, v196
	v_add_u32_e32 v199, 0, v2
	s_mov_b32 s6, s7
	s_barrier
	s_branch .LBB0_1299

.LBB0_1309:
	s_add_u32 s51, s26, 0x100
	s_addc_u32 s52, s27, 0
	s_mov_b32 s53, -2
	ds_read_b128 v[128:131], v197
	ds_read_b128 v[132:135], v197 offset:1024
	ds_read_b128 v[136:139], v197 offset:2048
	ds_read_b128 v[140:143], v197 offset:3072
	ds_read_b128 v[144:147], v198
	ds_read_b128 v[148:151], v198 offset:1024
	ds_read_b128 v[152:155], v198 offset:2048
	ds_read_b128 v[156:159], v198 offset:3072
	s_add_u32 s4, s24, 0x100
	s_addc_u32 s5, s25, 0
	s_cmp_eq_u32 s53, 40
	s_cselect_b32 s29, s21, s5
	s_cselect_b32 s28, s20, s4
	s_cselect_b32 s27, s23, s52
	s_cselect_b32 s26, s22, s51
	v_lshl_add_u64 v[212:213], s[24:25], 0, v[172:173]
	s_add_i32 m0, s36, 0xc000
	ds_read_b128 v[160:163], v199
	ds_read_b128 v[180:183], v199 offset:1024
	ds_read_b128 v[184:187], v199 offset:2048
	ds_read_b128 v[188:191], v199 offset:3072
	ds_read_b128 v[192:195], v199 offset:4096
	ds_read_b128 v[200:203], v199 offset:5120
	ds_read_b128 v[204:207], v199 offset:6144
	ds_read_b128 v[208:211], v199 offset:7168
	global_load_lds_dwordx4 v[212:213], off
	s_add_i32 m0, s36, 0xe000
	v_lshl_add_u64 v[212:213], s[24:25], 0, v[174:175]
	global_load_lds_dwordx4 v[212:213], off
	s_waitcnt lgkmcnt(0)
	s_barrier
	s_setprio 1
	v_mfma_f32_16x16x32_bf16 v[124:127], v[128:131], v[160:163], 0
	v_mfma_f32_16x16x32_bf16 v[120:123], v[136:139], v[160:163], 0
	v_mfma_f32_16x16x32_bf16 v[116:119], v[128:131], v[184:187], 0
	v_mfma_f32_16x16x32_bf16 v[108:111], v[136:139], v[184:187], 0
	v_mfma_f32_16x16x32_bf16 v[88:91], v[128:131], v[192:195], 0
	v_mfma_f32_16x16x32_bf16 v[100:103], v[136:139], v[192:195], 0
	v_mfma_f32_16x16x32_bf16 v[72:75], v[128:131], v[204:207], 0
	v_mfma_f32_16x16x32_bf16 v[76:79], v[136:139], v[204:207], 0
	v_mfma_f32_16x16x32_bf16 v[124:127], v[132:135], v[180:183], v[124:127]
	v_mfma_f32_16x16x32_bf16 v[120:123], v[140:143], v[180:183], v[120:123]
	v_mfma_f32_16x16x32_bf16 v[116:119], v[132:135], v[188:191], v[116:119]
	v_mfma_f32_16x16x32_bf16 v[108:111], v[140:143], v[188:191], v[108:111]
	v_mfma_f32_16x16x32_bf16 v[88:91], v[132:135], v[200:203], v[88:91]
	v_mfma_f32_16x16x32_bf16 v[100:103], v[140:143], v[200:203], v[100:103]
	v_mfma_f32_16x16x32_bf16 v[72:75], v[132:135], v[208:211], v[72:75]
	v_mfma_f32_16x16x32_bf16 v[76:79], v[140:143], v[208:211], v[76:79]
	v_mfma_f32_16x16x32_bf16 v[112:115], v[144:147], v[160:163], 0
	v_mfma_f32_16x16x32_bf16 v[104:107], v[152:155], v[160:163], 0
	v_mfma_f32_16x16x32_bf16 v[96:99], v[144:147], v[184:187], 0
	v_mfma_f32_16x16x32_bf16 v[92:95], v[152:155], v[184:187], 0
	v_mfma_f32_16x16x32_bf16 v[80:83], v[144:147], v[192:195], 0
	v_mfma_f32_16x16x32_bf16 v[84:87], v[152:155], v[192:195], 0
	v_mfma_f32_16x16x32_bf16 v[64:67], v[144:147], v[204:207], 0
	v_mfma_f32_16x16x32_bf16 v[68:71], v[152:155], v[204:207], 0
	v_mfma_f32_16x16x32_bf16 v[112:115], v[148:151], v[180:183], v[112:115]
	v_mfma_f32_16x16x32_bf16 v[104:107], v[156:159], v[180:183], v[104:107]
	v_mfma_f32_16x16x32_bf16 v[96:99], v[148:151], v[188:191], v[96:99]
	v_mfma_f32_16x16x32_bf16 v[92:95], v[156:159], v[188:191], v[92:95]
	s_setprio 2
	s_barrier
	v_mfma_f32_16x16x32_bf16 v[80:83], v[148:151], v[200:203], v[80:83]
	v_mfma_f32_16x16x32_bf16 v[84:87], v[156:159], v[200:203], v[84:87]
	v_mfma_f32_16x16x32_bf16 v[64:67], v[148:151], v[208:211], v[64:67]
	v_mfma_f32_16x16x32_bf16 v[68:71], v[156:159], v[208:211], v[68:71]
	s_setprio 2
	s_add_i32 s24, s45, s35
	v_lshl_add_u64 v[212:213], s[26:27], 0, v[166:167]
	s_mov_b32 m0, s24
	ds_read_b128 v[160:163], v199 offset:16384
	ds_read_b128 v[180:183], v199 offset:17408
	ds_read_b128 v[184:187], v199 offset:18432
	ds_read_b128 v[188:191], v199 offset:19456
	ds_read_b128 v[192:195], v199 offset:20480
	ds_read_b128 v[200:203], v199 offset:21504
	ds_read_b128 v[204:207], v199 offset:22528
	ds_read_b128 v[208:211], v199 offset:23552
	global_load_lds_dwordx4 v[212:213], off
	s_add_i32 m0, s24, 0x2000
	s_add_u32 s24, s26, 0xb0000
	v_lshl_add_u64 v[214:215], s[26:27], 0, v[170:171]
	s_addc_u32 s25, s27, 0
	s_add_i32 s54, s46, s35
	global_load_lds_dwordx4 v[214:215], off
	v_lshl_add_u64 v[216:217], s[24:25], 0, v[166:167]
	s_mov_b32 m0, s54
	v_lshl_add_u64 v[218:219], s[28:29], 0, v[168:169]
	global_load_lds_dwordx4 v[216:217], off
	s_add_i32 m0, s54, 0x2000
	v_lshl_add_u64 v[216:217], s[24:25], 0, v[170:171]
	global_load_lds_dwordx4 v[216:217], off
	s_mov_b32 m0, s36
	v_lshl_add_u64 v[216:217], s[28:29], 0, v[164:165]
	global_load_lds_dwordx4 v[216:217], off
	s_mov_b32 m0, s37
	s_nop 0
	global_load_lds_dwordx4 v[218:219], off
	s_waitcnt lgkmcnt(0)
	s_barrier
	s_setprio 1
	v_mfma_f32_16x16x32_bf16 v[56:59], v[128:131], v[160:163], 0
	v_mfma_f32_16x16x32_bf16 v[60:63], v[136:139], v[160:163], 0
	v_mfma_f32_16x16x32_bf16 v[40:43], v[128:131], v[184:187], 0
	v_mfma_f32_16x16x32_bf16 v[44:47], v[136:139], v[184:187], 0
	v_mfma_f32_16x16x32_bf16 v[24:27], v[128:131], v[192:195], 0
	v_mfma_f32_16x16x32_bf16 v[28:31], v[136:139], v[192:195], 0
	v_mfma_f32_16x16x32_bf16 v[8:11], v[128:131], v[204:207], 0
	v_mfma_f32_16x16x32_bf16 v[12:15], v[136:139], v[204:207], 0
	v_mfma_f32_16x16x32_bf16 v[56:59], v[132:135], v[180:183], v[56:59]
	v_mfma_f32_16x16x32_bf16 v[60:63], v[140:143], v[180:183], v[60:63]
	v_mfma_f32_16x16x32_bf16 v[40:43], v[132:135], v[188:191], v[40:43]
	v_mfma_f32_16x16x32_bf16 v[44:47], v[140:143], v[188:191], v[44:47]
	v_mfma_f32_16x16x32_bf16 v[24:27], v[132:135], v[200:203], v[24:27]
	v_mfma_f32_16x16x32_bf16 v[28:31], v[140:143], v[200:203], v[28:31]
	v_mfma_f32_16x16x32_bf16 v[8:11], v[132:135], v[208:211], v[8:11]
	v_mfma_f32_16x16x32_bf16 v[12:15], v[140:143], v[208:211], v[12:15]
	v_mfma_f32_16x16x32_bf16 v[48:51], v[144:147], v[160:163], 0
	v_mfma_f32_16x16x32_bf16 v[52:55], v[152:155], v[160:163], 0
	v_mfma_f32_16x16x32_bf16 v[32:35], v[144:147], v[184:187], 0
	v_mfma_f32_16x16x32_bf16 v[36:39], v[152:155], v[184:187], 0
	v_mfma_f32_16x16x32_bf16 v[16:19], v[144:147], v[192:195], 0
	v_mfma_f32_16x16x32_bf16 v[20:23], v[152:155], v[192:195], 0
	v_mfma_f32_16x16x32_bf16 v[0:3], v[144:147], v[204:207], 0
	v_mfma_f32_16x16x32_bf16 v[4:7], v[152:155], v[204:207], 0
	v_mfma_f32_16x16x32_bf16 v[48:51], v[148:151], v[180:183], v[48:51]
	v_mfma_f32_16x16x32_bf16 v[52:55], v[156:159], v[180:183], v[52:55]
	v_mfma_f32_16x16x32_bf16 v[32:35], v[148:151], v[188:191], v[32:35]
	v_mfma_f32_16x16x32_bf16 v[36:39], v[156:159], v[188:191], v[36:39]
	s_setprio 2
	s_barrier
	v_mfma_f32_16x16x32_bf16 v[16:19], v[148:151], v[200:203], v[16:19]
	v_mfma_f32_16x16x32_bf16 v[20:23], v[156:159], v[200:203], v[20:23]
	v_mfma_f32_16x16x32_bf16 v[0:3], v[148:151], v[208:211], v[0:3]
	v_mfma_f32_16x16x32_bf16 v[4:7], v[156:159], v[208:211], v[4:7]
	s_setprio 0
	s_add_i32 s54, 0, 0x18000
	s_add_i32 s55, 0, 0x1c000
	v_add_u32_e32 v140, s54, v196
	v_add_u32_e32 v156, s55, v196
	ds_read_b128 v[128:131], v140
	ds_read_b128 v[132:135], v140 offset:1024
	ds_read_b128 v[136:139], v140 offset:2048
	ds_read_b128 v[140:143], v140 offset:3072
	ds_read_b128 v[144:147], v156
	ds_read_b128 v[148:151], v156 offset:1024
	ds_read_b128 v[152:155], v156 offset:2048
	ds_read_b128 v[156:159], v156 offset:3072
	s_add_u32 s24, s28, 0xb0000
	s_addc_u32 s25, s29, 0
	s_mov_b32 m0, s38
	v_lshl_add_u64 v[220:221], s[24:25], 0, v[164:165]
	ds_read_b128 v[160:163], v199 offset:32768
	ds_read_b128 v[180:183], v199 offset:33792
	ds_read_b128 v[184:187], v199 offset:34816
	ds_read_b128 v[188:191], v199 offset:35840
	ds_read_b128 v[192:195], v199 offset:36864
	ds_read_b128 v[200:203], v199 offset:37888
	ds_read_b128 v[204:207], v199 offset:38912
	ds_read_b128 v[208:211], v199 offset:39936
	global_load_lds_dwordx4 v[220:221], off
	s_mov_b32 m0, s39
	v_lshl_add_u64 v[220:221], s[24:25], 0, v[168:169]
	global_load_lds_dwordx4 v[220:221], off
	s_waitcnt vmcnt(8) lgkmcnt(0)
	s_barrier
	s_setprio 1
	v_mfma_f32_16x16x32_bf16 v[124:127], v[128:131], v[160:163], v[124:127]
	v_mfma_f32_16x16x32_bf16 v[120:123], v[136:139], v[160:163], v[120:123]
	v_mfma_f32_16x16x32_bf16 v[116:119], v[128:131], v[184:187], v[116:119]
	v_mfma_f32_16x16x32_bf16 v[108:111], v[136:139], v[184:187], v[108:111]
	v_mfma_f32_16x16x32_bf16 v[88:91], v[128:131], v[192:195], v[88:91]
	v_mfma_f32_16x16x32_bf16 v[100:103], v[136:139], v[192:195], v[100:103]
	v_mfma_f32_16x16x32_bf16 v[72:75], v[128:131], v[204:207], v[72:75]
	v_mfma_f32_16x16x32_bf16 v[76:79], v[136:139], v[204:207], v[76:79]
	v_mfma_f32_16x16x32_bf16 v[124:127], v[132:135], v[180:183], v[124:127]
	v_mfma_f32_16x16x32_bf16 v[120:123], v[140:143], v[180:183], v[120:123]
	v_mfma_f32_16x16x32_bf16 v[116:119], v[132:135], v[188:191], v[116:119]
	v_mfma_f32_16x16x32_bf16 v[108:111], v[140:143], v[188:191], v[108:111]
	v_mfma_f32_16x16x32_bf16 v[88:91], v[132:135], v[200:203], v[88:91]
	v_mfma_f32_16x16x32_bf16 v[100:103], v[140:143], v[200:203], v[100:103]
	v_mfma_f32_16x16x32_bf16 v[72:75], v[132:135], v[208:211], v[72:75]
	v_mfma_f32_16x16x32_bf16 v[76:79], v[140:143], v[208:211], v[76:79]
	v_mfma_f32_16x16x32_bf16 v[112:115], v[144:147], v[160:163], v[112:115]
	v_mfma_f32_16x16x32_bf16 v[104:107], v[152:155], v[160:163], v[104:107]
	v_mfma_f32_16x16x32_bf16 v[96:99], v[144:147], v[184:187], v[96:99]
	v_mfma_f32_16x16x32_bf16 v[92:95], v[152:155], v[184:187], v[92:95]
	v_mfma_f32_16x16x32_bf16 v[80:83], v[144:147], v[192:195], v[80:83]
	v_mfma_f32_16x16x32_bf16 v[84:87], v[152:155], v[192:195], v[84:87]
	v_mfma_f32_16x16x32_bf16 v[64:67], v[144:147], v[204:207], v[64:67]
	v_mfma_f32_16x16x32_bf16 v[68:71], v[152:155], v[204:207], v[68:71]
	v_mfma_f32_16x16x32_bf16 v[112:115], v[148:151], v[180:183], v[112:115]
	v_mfma_f32_16x16x32_bf16 v[104:107], v[156:159], v[180:183], v[104:107]
	v_mfma_f32_16x16x32_bf16 v[96:99], v[148:151], v[188:191], v[96:99]
	v_mfma_f32_16x16x32_bf16 v[92:95], v[156:159], v[188:191], v[92:95]
	s_setprio 2
	s_barrier
	v_mfma_f32_16x16x32_bf16 v[80:83], v[148:151], v[200:203], v[80:83]
	v_mfma_f32_16x16x32_bf16 v[84:87], v[156:159], v[200:203], v[84:87]
	v_mfma_f32_16x16x32_bf16 v[64:67], v[148:151], v[208:211], v[64:67]
	v_mfma_f32_16x16x32_bf16 v[68:71], v[156:159], v[208:211], v[68:71]
	s_setprio 2
	s_add_i32 s24, s54, s35
	v_lshl_add_u64 v[212:213], v[212:213], 0, s[16:17]
	s_mov_b32 m0, s24
	ds_read_b128 v[160:163], v199 offset:49152
	ds_read_b128 v[180:183], v199 offset:50176
	ds_read_b128 v[184:187], v199 offset:51200
	ds_read_b128 v[188:191], v199 offset:52224
	ds_read_b128 v[192:195], v199 offset:53248
	ds_read_b128 v[200:203], v199 offset:54272
	ds_read_b128 v[204:207], v199 offset:55296
	ds_read_b128 v[208:211], v199 offset:56320
	global_load_lds_dwordx4 v[212:213], off
	s_add_i32 m0, s24, 0x2000
	s_add_u32 s24, s26, 0xb0080
	v_lshl_add_u64 v[212:213], v[214:215], 0, s[16:17]
	s_addc_u32 s25, s27, 0
	s_add_i32 s26, s55, s35
	global_load_lds_dwordx4 v[212:213], off
	s_mov_b32 m0, s26
	v_lshl_add_u64 v[212:213], s[24:25], 0, v[166:167]
	global_load_lds_dwordx4 v[212:213], off
	s_add_i32 m0, s26, 0x2000
	v_lshl_add_u64 v[212:213], s[24:25], 0, v[170:171]
	global_load_lds_dwordx4 v[212:213], off
	s_mov_b32 m0, s41
	v_lshl_add_u64 v[212:213], v[216:217], 0, s[16:17]
	global_load_lds_dwordx4 v[212:213], off
	s_mov_b32 m0, s42
	v_lshl_add_u64 v[212:213], v[218:219], 0, s[16:17]
	global_load_lds_dwordx4 v[212:213], off
	s_waitcnt vmcnt(8) lgkmcnt(0)
	s_barrier
	s_setprio 1
	v_mfma_f32_16x16x32_bf16 v[56:59], v[128:131], v[160:163], v[56:59]
	v_mfma_f32_16x16x32_bf16 v[60:63], v[136:139], v[160:163], v[60:63]
	v_mfma_f32_16x16x32_bf16 v[40:43], v[128:131], v[184:187], v[40:43]
	v_mfma_f32_16x16x32_bf16 v[44:47], v[136:139], v[184:187], v[44:47]
	v_mfma_f32_16x16x32_bf16 v[24:27], v[128:131], v[192:195], v[24:27]
	v_mfma_f32_16x16x32_bf16 v[28:31], v[136:139], v[192:195], v[28:31]
	v_mfma_f32_16x16x32_bf16 v[8:11], v[128:131], v[204:207], v[8:11]
	v_mfma_f32_16x16x32_bf16 v[12:15], v[136:139], v[204:207], v[12:15]
	v_mfma_f32_16x16x32_bf16 v[56:59], v[132:135], v[180:183], v[56:59]
	v_mfma_f32_16x16x32_bf16 v[60:63], v[140:143], v[180:183], v[60:63]
	v_mfma_f32_16x16x32_bf16 v[40:43], v[132:135], v[188:191], v[40:43]
	v_mfma_f32_16x16x32_bf16 v[44:47], v[140:143], v[188:191], v[44:47]
	v_mfma_f32_16x16x32_bf16 v[24:27], v[132:135], v[200:203], v[24:27]
	v_mfma_f32_16x16x32_bf16 v[28:31], v[140:143], v[200:203], v[28:31]
	v_mfma_f32_16x16x32_bf16 v[8:11], v[132:135], v[208:211], v[8:11]
	v_mfma_f32_16x16x32_bf16 v[12:15], v[140:143], v[208:211], v[12:15]
	v_mfma_f32_16x16x32_bf16 v[48:51], v[144:147], v[160:163], v[48:51]
	v_mfma_f32_16x16x32_bf16 v[52:55], v[152:155], v[160:163], v[52:55]
	v_mfma_f32_16x16x32_bf16 v[32:35], v[144:147], v[184:187], v[32:35]
	v_mfma_f32_16x16x32_bf16 v[36:39], v[152:155], v[184:187], v[36:39]
	v_mfma_f32_16x16x32_bf16 v[16:19], v[144:147], v[192:195], v[16:19]
	v_mfma_f32_16x16x32_bf16 v[20:23], v[152:155], v[192:195], v[20:23]
	v_mfma_f32_16x16x32_bf16 v[0:3], v[144:147], v[204:207], v[0:3]
	v_mfma_f32_16x16x32_bf16 v[4:7], v[152:155], v[204:207], v[4:7]
	v_mfma_f32_16x16x32_bf16 v[48:51], v[148:151], v[180:183], v[48:51]
	v_mfma_f32_16x16x32_bf16 v[52:55], v[156:159], v[180:183], v[52:55]
	v_mfma_f32_16x16x32_bf16 v[32:35], v[148:151], v[188:191], v[32:35]
	v_mfma_f32_16x16x32_bf16 v[36:39], v[156:159], v[188:191], v[36:39]
	s_setprio 2
	s_barrier
	v_mfma_f32_16x16x32_bf16 v[16:19], v[148:151], v[200:203], v[16:19]
	v_mfma_f32_16x16x32_bf16 v[20:23], v[156:159], v[200:203], v[20:23]
	v_mfma_f32_16x16x32_bf16 v[0:3], v[148:151], v[208:211], v[0:3]
	v_mfma_f32_16x16x32_bf16 v[4:7], v[156:159], v[208:211], v[4:7]
	s_setprio 0
	s_add_i32 s53, s53, 2
	s_add_u32 s51, s51, 0x100
	s_addc_u32 s52, s52, 0
	s_cmp_gt_u32 s53, 41
	s_mov_b64 s[24:25], s[4:5]
